# stack4: + K/V-path bias hoist in P1 epilogue + ev sel_i/cbuf loads via SGPR bases
# baseline (speedup 1.0000x reference)
; DI void inproj_epilogue(const Params& p, const char* smem, const int m0, const int n0) {
;     ...
;   } else {
;     const int cc0 = n0 - 2048;
; #pragma unroll 2
;     for (int i = 0; i < 8; ++i) {
;       const int q = threadIdx.x + NT * i, col = q & 127, cidx = q >> 7;
;       const float bias = p.b_in[n0 + col];
;       const int cc = cc0 + col, bh = bbase + (cc >> 6), d = cc & 63;
;     ...
;       V_CHUNK(1, vT);
;       V_CHUNK(4, vT4);
;       V_CHUNK(16, vT16);
;     ...
;     }
.LBB0_72:
	s_cmp_gt_i32 s4, 5
	s_mov_b64 s[82:83], -1
	s_waitcnt vmcnt(0) lgkmcnt(0)
	s_barrier
	s_cbranch_scc0 .LBB0_81
	s_and_b32 s8, s43, -8
	s_and_b32 s5, s80, 0x700
	s_cmpk_gt_u32 s78, 0x7ff
	s_cbranch_scc0 .LBB0_77
	v_add_u32_e32 v152, s78, v167
	v_or_b32_e32 v130, s78, v166
	v_lshrrev_b32_e32 v153, 6, v152
	v_lshlrev_b32_e32 v152, 4, v152
	v_add_lshl_u32 v157, v153, s8, 7
	v_and_b32_e32 v154, 0x3f0, v152
	v_lshl_add_u64 v[152:153], v[130:131], 2, s[56:57]
	v_add_lshl_u32 v130, v167, s78, 1
	v_and_b32_e32 v158, 0xffffff80, v130
	v_add_u32_e32 v130, s5, v179
	v_lshrrev_b32_e32 v155, 6, v130
	s_lshl_b32 s0, s43, 7
	v_lshrrev_b32_e32 v160, 2, v130
	v_add_u32_e32 v130, s5, v186
	s_and_b32 s0, s0, 0xfffffc00
	v_lshrrev_b32_e32 v130, 4, v130
	v_or_b32_e32 v161, s0, v130
	v_add_u32_e32 v130, s5, v188
	v_lshrrev_b32_e32 v130, 4, v130
	v_add_u32_e32 v155, v177, v155
	v_or_b32_e32 v204, s0, v130
	v_add_u32_e32 v130, s5, v169
	v_or_b32_e32 v159, s0, v155
	v_lshrrev_b32_e32 v155, 6, v130
	v_add_u32_e32 v155, v177, v155
	v_or_b32_e32 v205, s0, v155
	v_lshrrev_b32_e32 v206, 2, v130
	s_mov_b32 s46, 0
	v_lshlrev_b32_e32 v154, 1, v154
	v_mov_b32_e32 v207, v187
	v_mov_b32_e32 v208, v169
	v_mov_b32_e32 v209, v185
	v_mov_b32_e32 v210, v184
	global_load_dword v240, v[152:153], off
	s_waitcnt vmcnt(0)
.LBB0_75:
	s_nop 0
	v_add_u32_e32 v155, 0x400, v207
	ds_read2_b32 v[214:215], v155 offset0:8 offset1:140
	v_add_u32_e32 v155, 0x800, v207
	ds_read2_b32 v[212:213], v207 offset1:132
	ds_read2_b32 v[216:217], v155 offset0:16 offset1:148
	v_add_u32_e32 v155, 0xc00, v207
	ds_read2_b32 v[218:219], v155 offset0:24 offset1:156
	v_add_u32_e32 v130, s46, v188
	v_and_b32_e32 v130, 8, v130
	v_lshlrev_b32_e32 v130, 1, v130
	v_mov_b32_e32 v155, v131
	v_add_u32_e32 v211, s46, v149
	v_and_b32_e32 v211, 0x180, v211
	v_add_u32_e32 v207, 0x8400, v207
	s_waitcnt lgkmcnt(2)
	v_pk_add_f32 v[212:213], v[240:241], v[212:213] op_sel_hi:[0,1]
	v_pk_add_f32 v[214:215], v[240:241], v[214:215] op_sel_hi:[0,1]
	s_waitcnt lgkmcnt(1)
	v_pk_add_f32 v[216:217], v[240:241], v[216:217] op_sel_hi:[0,1]
	v_cvt_pk_bf16_f32 v212, v212, v213
	v_cvt_pk_bf16_f32 v213, v214, v215
	v_cvt_pk_bf16_f32 v214, v216, v217
	v_add_u32_e32 v216, v158, v204
	v_ashrrev_i32_e32 v217, 31, v216
	v_lshlrev_b64 v[216:217], 11, v[216:217]
	v_lshl_add_u64 v[216:217], s[20:21], 0, v[216:217]
	s_waitcnt lgkmcnt(0)
	v_pk_add_f32 v[218:219], v[240:241], v[218:219] op_sel_hi:[0,1]
	v_lshl_add_u64 v[216:217], v[216:217], 0, v[130:131]
	v_cvt_pk_bf16_f32 v215, v218, v219
	v_lshl_add_u64 v[216:217], v[216:217], 0, v[154:155]
	global_store_dwordx4 v[216:217], v[212:215], off
	v_add_u32_e32 v130, s46, v169
	v_add_u32_e32 v217, s46, v172
	v_add_u32_e32 v213, s46, v170
	v_add_u32_e32 v215, s46, v171
	v_mad_u32_u24 v130, v130, s41, v168
	v_mad_u32_u24 v213, v213, s41, v168
	v_mad_u32_u24 v215, v215, s41, v168
	v_mad_u32_u24 v217, v217, s41, v168
	ds_read_b32 v212, v130
	ds_read_b32 v214, v130 offset:4224
	ds_read_b32 v215, v215
	ds_read_b32 v216, v130 offset:8448
	ds_read_b32 v218, v130 offset:12672
	ds_read_b32 v213, v213
	ds_read_b32 v217, v217
	v_add_u32_e32 v130, s46, v173
	v_mad_u32_u24 v130, v130, s41, v168
	s_waitcnt lgkmcnt(4)
	v_pk_add_f32 v[214:215], v[240:241], v[214:215] op_sel_hi:[0,1]
	ds_read_b32 v219, v130
	s_waitcnt lgkmcnt(2)
	v_pk_add_f32 v[212:213], v[240:241], v[212:213] op_sel_hi:[0,1]
	s_waitcnt lgkmcnt(1)
	v_pk_add_f32 v[216:217], v[240:241], v[216:217] op_sel_hi:[0,1]
	v_cvt_pk_bf16_f32 v212, v212, v213
	v_cvt_pk_bf16_f32 v213, v214, v215
	v_cvt_pk_bf16_f32 v214, v216, v217
	v_add_u32_e32 v216, v158, v205
	v_ashrrev_i32_e32 v217, 31, v216
	v_and_b32_e32 v130, 8, v206
	v_lshlrev_b64 v[216:217], 11, v[216:217]
	v_lshl_add_u64 v[216:217], s[22:23], 0, v[216:217]
	v_lshlrev_b32_e32 v130, 1, v130
	s_waitcnt lgkmcnt(0)
	v_pk_add_f32 v[218:219], v[240:241], v[218:219] op_sel_hi:[0,1]
	v_lshl_add_u64 v[216:217], v[216:217], 0, v[130:131]
	v_cvt_pk_bf16_f32 v215, v218, v219
	v_lshl_add_u64 v[216:217], v[216:217], 0, v[154:155]
	v_and_b32_e32 v130, 15, v208
	global_store_dwordx4 v[216:217], v[212:215], off
	v_add_u32_e32 v208, 8, v208
	v_add_u32_e32 v204, 4, v204
	v_or_b32_e32 v212, v211, v130
	v_mad_u32_u24 v218, v212, s41, v168
	ds_read2st64_b32 v[212:213], v218 offset1:33
	ds_read2st64_b32 v[214:215], v218 offset0:66 offset1:99
	ds_read2st64_b32 v[216:217], v218 offset0:132 offset1:165
	ds_read2st64_b32 v[218:219], v218 offset0:198 offset1:231
	v_or_b32_e32 v130, s5, v130
	v_add_u32_e32 v130, v130, v211
	s_waitcnt lgkmcnt(3)
	v_pk_add_f32 v[212:213], v[240:241], v[212:213] op_sel_hi:[0,1]
	s_waitcnt lgkmcnt(2)
	v_pk_add_f32 v[214:215], v[240:241], v[214:215] op_sel_hi:[0,1]
	s_waitcnt lgkmcnt(1)
	v_pk_add_f32 v[216:217], v[240:241], v[216:217] op_sel_hi:[0,1]
	s_waitcnt lgkmcnt(0)
	v_pk_add_f32 v[218:219], v[240:241], v[218:219] op_sel_hi:[0,1]
	v_lshlrev_b32_e32 v156, 3, v130
	v_lshrrev_b32_e32 v211, 8, v130
	v_and_b32_e32 v156, 0x78, v156
	v_or_b32_e32 v211, v211, v157
	v_cvt_pk_bf16_f32 v212, v212, v213
	v_cvt_pk_bf16_f32 v213, v214, v215
	v_cvt_pk_bf16_f32 v214, v216, v217
	v_add_u32_e32 v216, v211, v156
	v_ashrrev_i32_e32 v217, 31, v216
	v_lshlrev_b64 v[216:217], 11, v[216:217]
	v_lshrrev_b32_e32 v130, 3, v130
	v_lshl_add_u64 v[216:217], s[24:25], 0, v[216:217]
	v_and_b32_e32 v130, 16, v130
	v_lshl_add_u64 v[216:217], v[216:217], 0, v[130:131]
	v_cvt_pk_bf16_f32 v215, v218, v219
	v_lshl_add_u64 v[216:217], v[216:217], 0, v[154:155]
	global_store_dwordx4 v[216:217], v[212:215], off
	s_nop 0
	v_add_u32_e32 v211, 0x400, v209
	ds_read2_b32 v[214:215], v211 offset0:8 offset1:140
	v_add_u32_e32 v211, 0x800, v209
	ds_read2_b32 v[212:213], v209 offset1:132
	ds_read2_b32 v[216:217], v211 offset0:16 offset1:148
	v_add_u32_e32 v211, 0xc00, v209
	ds_read2_b32 v[218:219], v211 offset0:24 offset1:156
	v_add_u32_e32 v130, s46, v186
	v_and_b32_e32 v130, 8, v130
	v_lshlrev_b32_e32 v130, 1, v130
	v_add_u32_e32 v211, s46, v178
	v_and_b32_e32 v211, 0x180, v211
	v_add_u32_e32 v209, 0x8400, v209
	v_add_u32_e32 v205, 1, v205
	v_add_u32_e32 v206, 16, v206
	s_waitcnt lgkmcnt(2)
; DI void inproj_epilogue(const Params& p, const char* smem, const int m0, const int n0) {
;     ...
;     for (int i = 0; i < 8; ++i) {
;       const int q = threadIdx.x + NT * i, col = q & 127, cidx = q >> 7;
;       const float bias = p.b_in[n0 + col];
;       const int cc = cc0 + col, bh = bbase + (cc >> 6), d = cc & 63;
;     ...
;       V_CHUNK(1, vT);
;       V_CHUNK(4, vT4);
;       V_CHUNK(16, vT16);
;     ...
;     }
	v_pk_add_f32 v[212:213], v[240:241], v[212:213] op_sel_hi:[0,1]
	v_pk_add_f32 v[214:215], v[240:241], v[214:215] op_sel_hi:[0,1]
	s_waitcnt lgkmcnt(1)
	v_pk_add_f32 v[216:217], v[240:241], v[216:217] op_sel_hi:[0,1]
	v_cvt_pk_bf16_f32 v212, v212, v213
	v_cvt_pk_bf16_f32 v213, v214, v215
	v_cvt_pk_bf16_f32 v214, v216, v217
	v_add_u32_e32 v216, v158, v161
	v_ashrrev_i32_e32 v217, 31, v216
	v_lshlrev_b64 v[216:217], 11, v[216:217]
	v_lshl_add_u64 v[216:217], s[20:21], 0, v[216:217]
	s_waitcnt lgkmcnt(0)
	v_pk_add_f32 v[218:219], v[240:241], v[218:219] op_sel_hi:[0,1]
	v_lshl_add_u64 v[216:217], v[216:217], 0, v[130:131]
	v_cvt_pk_bf16_f32 v215, v218, v219
	v_lshl_add_u64 v[216:217], v[216:217], 0, v[154:155]
	global_store_dwordx4 v[216:217], v[212:215], off
	v_add_u32_e32 v130, s46, v179
	v_add_u32_e32 v217, s46, v181
	v_add_u32_e32 v213, s46, v183
	v_add_u32_e32 v215, s46, v182
	v_mad_u32_u24 v130, v130, s41, v168
	v_mad_u32_u24 v213, v213, s41, v168
	v_mad_u32_u24 v215, v215, s41, v168
	v_mad_u32_u24 v217, v217, s41, v168
	ds_read_b32 v212, v130
	ds_read_b32 v214, v130 offset:4224
	ds_read_b32 v215, v215
	ds_read_b32 v216, v130 offset:8448
	ds_read_b32 v218, v130 offset:12672
	ds_read_b32 v213, v213
	ds_read_b32 v217, v217
	v_add_u32_e32 v130, s46, v180
	v_mad_u32_u24 v130, v130, s41, v168
	s_waitcnt lgkmcnt(4)
	v_pk_add_f32 v[214:215], v[240:241], v[214:215] op_sel_hi:[0,1]
	ds_read_b32 v219, v130
	s_waitcnt lgkmcnt(2)
	v_pk_add_f32 v[212:213], v[240:241], v[212:213] op_sel_hi:[0,1]
	s_waitcnt lgkmcnt(1)
	v_pk_add_f32 v[216:217], v[240:241], v[216:217] op_sel_hi:[0,1]
	v_cvt_pk_bf16_f32 v212, v212, v213
	v_cvt_pk_bf16_f32 v213, v214, v215
	v_cvt_pk_bf16_f32 v214, v216, v217
	v_add_u32_e32 v216, v158, v159
	v_ashrrev_i32_e32 v217, 31, v216
	v_and_b32_e32 v130, 8, v160
	v_lshlrev_b64 v[216:217], 11, v[216:217]
	v_lshl_add_u64 v[216:217], s[22:23], 0, v[216:217]
	v_lshlrev_b32_e32 v130, 1, v130
	s_waitcnt lgkmcnt(0)
	v_pk_add_f32 v[218:219], v[240:241], v[218:219] op_sel_hi:[0,1]
	v_lshl_add_u64 v[216:217], v[216:217], 0, v[130:131]
	v_cvt_pk_bf16_f32 v215, v218, v219
	v_lshl_add_u64 v[216:217], v[216:217], 0, v[154:155]
	v_and_b32_e32 v130, 15, v210
	global_store_dwordx4 v[216:217], v[212:215], off
	s_add_i32 s46, s46, 64
	v_add_u32_e32 v159, 1, v159
	v_or_b32_e32 v212, v211, v130
	v_mad_u32_u24 v218, v212, s41, v168
	ds_read2st64_b32 v[212:213], v218 offset1:33
	ds_read2st64_b32 v[214:215], v218 offset0:66 offset1:99
	ds_read2st64_b32 v[216:217], v218 offset0:132 offset1:165
	ds_read2st64_b32 v[218:219], v218 offset0:198 offset1:231
	v_or_b32_e32 v130, s5, v130
	v_add_u32_e32 v130, v130, v211
	s_waitcnt lgkmcnt(3)
	v_pk_add_f32 v[212:213], v[240:241], v[212:213] op_sel_hi:[0,1]
	s_waitcnt lgkmcnt(2)
	v_pk_add_f32 v[214:215], v[240:241], v[214:215] op_sel_hi:[0,1]
	s_waitcnt lgkmcnt(1)
	v_pk_add_f32 v[216:217], v[240:241], v[216:217] op_sel_hi:[0,1]
	s_waitcnt lgkmcnt(0)
	v_pk_add_f32 v[218:219], v[240:241], v[218:219] op_sel_hi:[0,1]
	v_lshlrev_b32_e32 v156, 3, v130
	v_lshrrev_b32_e32 v211, 8, v130
	v_and_b32_e32 v156, 0x78, v156
	v_or_b32_e32 v211, v211, v157
	v_cvt_pk_bf16_f32 v212, v212, v213
	v_cvt_pk_bf16_f32 v213, v214, v215
	v_cvt_pk_bf16_f32 v214, v216, v217
	v_add_u32_e32 v216, v211, v156
	v_ashrrev_i32_e32 v217, 31, v216
	v_lshlrev_b64 v[216:217], 11, v[216:217]
	v_lshrrev_b32_e32 v130, 3, v130
	v_lshl_add_u64 v[216:217], s[24:25], 0, v[216:217]
	v_and_b32_e32 v130, 16, v130
	v_lshl_add_u64 v[216:217], v[216:217], 0, v[130:131]
	v_cvt_pk_bf16_f32 v215, v218, v219
	v_lshl_add_u64 v[216:217], v[216:217], 0, v[154:155]
	v_add_u32_e32 v160, 16, v160
	v_add_u32_e32 v210, 8, v210
	v_add_u32_e32 v161, 4, v161
	s_cmpk_lg_i32 s46, 0x100
	global_store_dwordx4 v[216:217], v[212:215], off
	s_cbranch_scc1 .LBB0_75
	s_mov_b64 s[82:83], 0
; DI unsigned pack2(float a, float b) { const f32x2 v = {a, b}; const bf16x2_t r = __builtin_convertvector(v, bf16x2_t); return __builtin_bit_cast(unsigned, r); }
; DI void inproj_epilogue(const Params& p, const char* smem, const int m0, const int n0) {
;     ...
;   if (n0 < 2048) {
;     const int cc0 = n0 - 1536;
; #pragma unroll 2
;     for (int i = 0; i < 8; ++i) {
;       const int q = threadIdx.x + NT * i, row = q >> 4, ch16 = q & 15;
;       const float4 y0 = *(const float4*)(ct + row * CT_PITCH + 8 * ch16), y1 = *(const float4*)(ct + row * CT_PITCH + 8 * ch16 + 4);
;       const float4 b0 = *(const float4*)(p.b_in + n0 + 8 * ch16), b1 = *(const float4*)(p.b_in + n0 + 8 * ch16 + 4);
;       uint4 r; r.x = pack2(y0.x + b0.x, y0.y + b0.y); r.y = pack2(y0.z + b0.z, y0.w + b0.w); r.z = pack2(y1.x + b1.x, y1.y + b1.y); r.w = pack2(y1.z + b1.z, y1.w + b1.w);
;       const int cc = cc0 + 8 * ch16, bh = bbase + (cc >> 6), d = cc & 63, s = s0 + row;
;       *(uint4*)(kb + attn_kidx<1>(bh, s, d)) = r;
;       *(uint4*)(k4 + attn_kidx<4>(bh, s, d)) = r;
;       *(uint4*)(k16 + attn_kidx<16>(bh, s, d)) = r;
;     }
.LBB0_77:
	s_and_b64 vcc, exec, s[82:83]
	s_cbranch_vccz .LBB0_80
	v_add_u32_e32 v130, s78, v174
	v_lshrrev_b32_e32 v152, 6, v130
	v_add_u32_e32 v152, s8, v152
	v_add_u32_e32 v154, s5, v178
	v_lshlrev_b32_e32 v156, 1, v130
	s_lshl_b32 s8, s43, 7
	v_and_b32_e32 v160, 0xffffff80, v156
	v_lshrrev_b32_e32 v156, 6, v154
	s_and_b32 s8, s8, 0xfffffc00
	v_or_b32_e32 v156, s8, v156
	v_and_b32_e32 v157, 0x60, v191
	v_add_u32_e32 v161, v156, v157
	v_lshrrev_b32_e32 v156, 4, v154
	v_add_u32_e32 v206, s5, v149
	v_or_b32_e32 v205, s8, v156
	v_lshrrev_b32_e32 v156, 6, v206
	v_lshlrev_b32_e32 v153, 4, v130
	v_or_b32_e32 v156, s8, v156
	v_and_b32_e32 v157, 0x60, v195
	v_lshlrev_b32_e32 v130, 5, v130
	s_and_b32 s1, s43, 7
	v_add_u32_e32 v207, v156, v157
	v_lshrrev_b32_e32 v156, 4, v206
	v_and_b32_e32 v130, 0x700, v130
	s_mov_b32 s79, s9
	v_and_b32_e32 v158, 0x380, v153
	s_lshl_b32 s0, s1, 9
	s_lshl_b32 s1, s1, 11
	v_or_b32_e32 v209, s8, v156
	v_lshl_add_u64 v[156:157], v[138:139], 0, v[130:131]
	v_or_b32_e32 v130, s8, v176
	v_lshl_or_b32 v155, v152, 7, v176
	v_lshl_add_u64 v[152:153], s[78:79], 2, v[134:135]
	v_or_b32_e32 v204, s1, v192
	v_or_b32_e32 v208, s1, v175
	v_add_u32_e32 v210, v130, v160
	s_mov_b64 s[82:83], 0
	v_lshlrev_b32_e32 v158, 1, v158
	v_mov_b32_e32 v211, v196
	v_mov_b32_e32 v212, v193
	v_mov_b32_e32 v213, v189
	global_load_dwordx4 v[240:243], v[152:153], off
	global_load_dwordx4 v[244:247], v[152:153], off offset:16
	s_waitcnt vmcnt(0)
.LBB0_79:
	s_nop 0
	s_nop 0
	ds_read_b128 v[222:225], v211
	ds_read_b128 v[226:229], v211 offset:16
	v_add_u32_e32 v230, v160, v209
	v_lshrrev_b32_e32 v130, 8, v206
	v_and_b32_e32 v233, 0x78, v208
	v_add_u32_e32 v232, v160, v207
	v_ashrrev_i32_e32 v231, 31, v230
	v_add_u32_e32 v235, s0, v194
	v_add_u32_e32 v234, v210, v130
	v_lshlrev_b32_e32 v130, 1, v233
	v_ashrrev_i32_e32 v233, 31, v232
	v_lshlrev_b64 v[230:231], 11, v[230:231]
	v_and_b32_e32 v236, 0x78, v235
	v_ashrrev_i32_e32 v235, 31, v234
	v_lshlrev_b64 v[232:233], 11, v[232:233]
	v_lshl_add_u64 v[230:231], s[18:19], 0, v[230:231]
	v_mov_b32_e32 v159, v131
	v_lshlrev_b64 v[234:235], 11, v[234:235]
	v_lshl_add_u64 v[232:233], s[26:27], 0, v[232:233]
	v_lshl_add_u64 v[230:231], v[230:231], 0, v[130:131]
	v_lshlrev_b32_e32 v130, 1, v236
	v_lshl_add_u64 v[234:235], v[156:157], 0, v[234:235]
	v_lshl_add_u64 v[230:231], v[230:231], 0, v[158:159]
	v_lshl_add_u64 v[232:233], v[232:233], 0, v[130:131]
	v_lshl_add_u64 v[234:235], v[234:235], 0, s[82:83]
	v_lshl_add_u64 v[232:233], v[232:233], 0, v[158:159]
	v_add_u32_e32 v130, s82, v154
	v_lshrrev_b32_e32 v130, 8, v130
	v_and_b32_e32 v236, 0x78, v204
	v_and_b32_e32 v237, 0x78, v213
	s_add_u32 s82, s82, 64
	s_addc_u32 s83, s83, 0
	v_add_u32_e32 v213, 32, v213
	v_add_u32_e32 v204, 0x200, v204
	v_add_u32_e32 v207, 1, v207
	v_add_u32_e32 v208, 0x200, v208
	v_add_u32_e32 v209, 4, v209
	v_add_u32_e32 v211, 0x8400, v211
	v_add_u32_e32 v206, 64, v206
	s_waitcnt lgkmcnt(1)
	v_pk_add_f32 v[214:215], v[222:223], v[240:241]
	v_pk_add_f32 v[216:217], v[224:225], v[242:243]
	s_waitcnt lgkmcnt(0)
	v_pk_add_f32 v[218:219], v[226:227], v[244:245]
	v_pk_add_f32 v[220:221], v[228:229], v[246:247]
	v_cvt_pk_bf16_f32 v214, v214, v215
	v_cvt_pk_bf16_f32 v215, v216, v217
	v_cvt_pk_bf16_f32 v216, v218, v219
	v_cvt_pk_bf16_f32 v217, v220, v221
	global_store_dwordx4 v[230:231], v[214:217], off
	global_store_dwordx4 v[232:233], v[214:217], off
	global_store_dwordx4 v[234:235], v[214:217], off offset:-8
	s_nop 0
	s_nop 0
	s_nop 0
	ds_read_b128 v[222:225], v212
	ds_read_b128 v[226:229], v212 offset:16
	v_add_u32_e32 v230, v160, v205
	v_add_u32_e32 v232, v160, v161
	v_add_u32_e32 v234, s0, v190
	v_ashrrev_i32_e32 v231, 31, v230
	v_ashrrev_i32_e32 v233, 31, v232
	v_and_b32_e32 v238, 0x78, v234
	v_lshlrev_b64 v[230:231], 11, v[230:231]
	v_add_u32_e32 v234, v155, v130
	v_lshlrev_b64 v[232:233], 11, v[232:233]
	v_lshl_add_u64 v[230:231], s[18:19], 0, v[230:231]
	v_ashrrev_i32_e32 v235, 31, v234
	v_lshlrev_b32_e32 v130, 1, v236
	v_lshl_add_u64 v[232:233], s[26:27], 0, v[232:233]
	v_lshlrev_b64 v[234:235], 11, v[234:235]
	v_lshl_add_u64 v[230:231], v[230:231], 0, v[130:131]
	v_lshlrev_b32_e32 v130, 1, v238
	v_lshl_add_u64 v[234:235], s[28:29], 0, v[234:235]
	s_addk_i32 s0, 0x80
	v_lshl_add_u64 v[232:233], v[232:233], 0, v[130:131]
	v_lshlrev_b32_e32 v130, 1, v237
	v_add_u32_e32 v161, 1, v161
	v_add_u32_e32 v205, 4, v205
	v_add_u32_e32 v212, 0x8400, v212
	v_lshl_add_u64 v[230:231], v[230:231], 0, v[158:159]
	s_cmpk_eq_i32 s82, 0x100
	v_lshl_add_u64 v[234:235], v[234:235], 0, v[130:131]
	v_lshl_add_u64 v[232:233], v[232:233], 0, v[158:159]
	v_lshl_add_u64 v[234:235], v[234:235], 0, v[158:159]
	s_waitcnt lgkmcnt(1)
	v_pk_add_f32 v[214:215], v[222:223], v[240:241]
	v_pk_add_f32 v[216:217], v[224:225], v[242:243]
	s_waitcnt lgkmcnt(0)
	v_pk_add_f32 v[218:219], v[226:227], v[244:245]
	v_pk_add_f32 v[220:221], v[228:229], v[246:247]
	v_cvt_pk_bf16_f32 v214, v214, v215
	v_cvt_pk_bf16_f32 v215, v216, v217
	v_cvt_pk_bf16_f32 v216, v218, v219
	v_cvt_pk_bf16_f32 v217, v220, v221
	global_store_dwordx4 v[230:231], v[214:217], off
	global_store_dwordx4 v[232:233], v[214:217], off
	global_store_dwordx4 v[234:235], v[214:217], off
	s_cbranch_scc0 .LBB0_79

; template <int D> DI size_t attn_vidx(int bh, int s, int d) {
;   const int r = s % D, l = s / D;
;   return ((size_t)((bh * D + r) * (128 / D) + (l >> 4)) * 64 + d) * 16 + (l & 15);
; }
; DI void inproj_epilogue(const Params& p, const char* smem, const int m0, const int n0) {
;     ...
;     const int cc0 = n0 - 2048;
; #pragma unroll 2
;     for (int i = 0; i < 8; ++i) {
;       const int q = threadIdx.x + NT * i, col = q & 127, cidx = q >> 7;
;       const float bias = p.b_in[n0 + col];
;       const int cc = cc0 + col, bh = bbase + (cc >> 6), d = cc & 63;
;     ...
;       V_CHUNK(1, vT);
;       V_CHUNK(4, vT4);
;       V_CHUNK(16, vT16);
.LBB0_90:
	s_or_b32 s82, s78, 0x80
	s_cmpk_gt_i32 s82, 0x5ff
	s_mov_b64 s[84:85], -1
	s_waitcnt lgkmcnt(0)
	s_barrier
	s_cbranch_scc0 .LBB0_99
	s_and_b32 s1, s43, -8
	s_and_b32 s0, s80, 0x700
	s_cmpk_gt_u32 s78, 0x7ff
	s_cbranch_scc0 .LBB0_95
	v_add_lshl_u32 v5, v203, s78, 1
	v_and_b32_e32 v16, 0xffffff80, v5
	v_add_u32_e32 v5, s0, v179
	v_lshrrev_b32_e32 v6, 6, v5
	s_lshl_b32 s4, s43, 7
	v_lshrrev_b32_e32 v18, 2, v5
	v_add_u32_e32 v5, s0, v186
	s_and_b32 s4, s4, 0xfffffc00
	v_lshrrev_b32_e32 v5, 4, v5
	v_or_b32_e32 v19, s4, v5
	v_add_u32_e32 v5, s0, v188
	v_lshrrev_b32_e32 v5, 4, v5
	v_add_u32_e32 v2, s82, v167
	v_add_u32_e32 v6, v177, v6
	v_or_b32_e32 v20, s4, v5
	v_add_u32_e32 v5, s0, v169
	v_lshrrev_b32_e32 v3, 6, v2
	v_lshlrev_b32_e32 v2, 4, v2
	v_or_b32_e32 v17, s4, v6
	v_lshrrev_b32_e32 v6, 6, v5
	v_and_b32_e32 v4, 0x3f0, v2
	v_add_u32_e32 v130, s78, v166
	v_add_u32_e32 v6, v177, v6
	v_add_lshl_u32 v7, v3, s1, 7
	v_lshl_add_u64 v[2:3], v[130:131], 2, s[56:57]
	v_or_b32_e32 v21, s4, v6
	v_lshrrev_b32_e32 v22, 2, v5
	s_mov_b32 s4, 0
	v_lshlrev_b32_e32 v4, 1, v4
	v_mov_b32_e32 v23, v187
	v_mov_b32_e32 v24, v169
	v_mov_b32_e32 v25, v185
	v_mov_b32_e32 v26, v184
	global_load_dword v240, v[2:3], off offset:512
	s_waitcnt vmcnt(0)
.LBB0_93:
	s_nop 0
	v_add_u32_e32 v15, s4, v188
	v_add_u32_e32 v11, 0x400, v23
	v_add_u32_e32 v27, 0x800, v23
	v_add_u32_e32 v32, 0xc00, v23
	v_add_u32_e32 v10, v16, v20
	v_add_u32_e32 v34, s4, v149
	v_add_u32_e32 v35, s4, v169
	v_add_u32_e32 v37, s4, v170
	v_add_u32_e32 v39, s4, v171
	v_add_u32_e32 v41, s4, v173
	v_and_b32_e32 v47, 15, v24
	ds_read2_b32 v[8:9], v23 offset1:132
	v_add_u32_e32 v40, s4, v172
	v_add_u32_e32 v14, v16, v21
	ds_read2_b32 v[12:13], v25 offset1:132
	ds_read2_b32 v[28:29], v11 offset0:8 offset1:140
	ds_read2_b32 v[30:31], v27 offset0:16 offset1:148
	ds_read2_b32 v[32:33], v32 offset0:24 offset1:156
	v_ashrrev_i32_e32 v11, 31, v10
	v_and_b32_e32 v27, 8, v15
	v_mad_u32_u24 v44, v35, s41, v168
	v_mad_u32_u24 v35, v37, s41, v168
	v_mad_u32_u24 v37, v39, s41, v168
	v_mad_u32_u24 v45, v41, s41, v168
	v_and_b32_e32 v48, 0x180, v34
	v_or_b32_e32 v49, s0, v47
	v_mad_u32_u24 v39, v40, s41, v168
	v_ashrrev_i32_e32 v15, 31, v14
	v_lshlrev_b64 v[10:11], 11, v[10:11]
	v_lshlrev_b32_e32 v130, 1, v27
	ds_read_b32 v34, v44
	ds_read_b32 v35, v35
	ds_read_b32 v40, v44 offset:4224
	ds_read_b32 v41, v37
	ds_read_b32 v42, v44 offset:8448
	ds_read_b32 v43, v39
	ds_read_b32 v45, v45
	ds_read_b32 v44, v44 offset:12672
	v_or_b32_e32 v27, v48, v47
	v_add_u32_e32 v37, v49, v48
	v_and_b32_e32 v46, 8, v22
	v_lshlrev_b64 v[14:15], 11, v[14:15]
	v_lshl_add_u64 v[10:11], s[20:21], 0, v[10:11]
	v_mad_u32_u24 v27, v27, s41, v168
	v_lshlrev_b32_e32 v39, 3, v37
	v_lshrrev_b32_e32 v54, 8, v37
	v_mov_b32_e32 v5, v131
	v_lshl_add_u64 v[14:15], s[22:23], 0, v[14:15]
	v_lshl_add_u64 v[10:11], v[10:11], 0, v[130:131]
	v_lshlrev_b32_e32 v130, 1, v46
	ds_read2st64_b32 v[46:47], v27 offset1:33
	ds_read2st64_b32 v[48:49], v27 offset0:66 offset1:99
	ds_read2st64_b32 v[50:51], v27 offset0:132 offset1:165
	ds_read2st64_b32 v[52:53], v27 offset0:198 offset1:231
	v_and_b32_e32 v27, 0x78, v39
	v_or_b32_e32 v39, v54, v7
	v_lshl_add_u64 v[54:55], v[10:11], 0, v[4:5]
	v_lshl_add_u64 v[10:11], v[14:15], 0, v[130:131]
	v_add_u32_e32 v14, v39, v27
	v_ashrrev_i32_e32 v15, 31, v14
	v_lshrrev_b32_e32 v37, 3, v37
	v_lshl_add_u64 v[56:57], v[10:11], 0, v[4:5]
	v_lshlrev_b64 v[10:11], 11, v[14:15]
	v_and_b32_e32 v130, 16, v37
	v_lshl_add_u64 v[10:11], s[24:25], 0, v[10:11]
	v_lshl_add_u64 v[10:11], v[10:11], 0, v[130:131]
	v_lshl_add_u64 v[14:15], v[10:11], 0, v[4:5]
	v_add_u32_e32 v36, v16, v19
	v_add_u32_e32 v62, s4, v178
	v_add_u32_e32 v63, s4, v179
	v_add_u32_e32 v64, s4, v183
	v_add_u32_e32 v65, s4, v182
	v_add_u32_e32 v66, s4, v181
	v_add_u32_e32 v67, s4, v180
	v_and_b32_e32 v69, 15, v26
	v_add_u32_e32 v59, 0x400, v25
	v_ashrrev_i32_e32 v37, 31, v36
	v_add_u32_e32 v60, 0x800, v25
	v_add_u32_e32 v61, 0xc00, v25
	v_add_u32_e32 v58, s4, v186
	v_add_u32_e32 v38, v16, v17
	v_and_b32_e32 v27, 8, v58
	v_ashrrev_i32_e32 v39, 31, v38
	v_and_b32_e32 v68, 8, v18
	v_lshlrev_b64 v[38:39], 11, v[38:39]
	v_lshlrev_b32_e32 v130, 1, v27
	v_lshl_add_u64 v[38:39], s[22:23], 0, v[38:39]
	s_add_i32 s4, s4, 64
	v_add_u32_e32 v17, 1, v17
	v_add_u32_e32 v18, 16, v18
	v_add_u32_e32 v26, 8, v26
	s_waitcnt lgkmcnt(14)
	v_pk_add_f32 v[8:9], v[240:241], v[8:9] op_sel_hi:[0,1]
	v_pk_add_f32 v[10:11], v[240:241], v[28:29] op_sel_hi:[0,1]
	s_waitcnt lgkmcnt(13)
	v_pk_add_f32 v[28:29], v[240:241], v[30:31] op_sel_hi:[0,1]
	s_waitcnt lgkmcnt(12)
	v_pk_add_f32 v[30:31], v[240:241], v[32:33] op_sel_hi:[0,1]
	s_waitcnt lgkmcnt(10)
	v_pk_add_f32 v[32:33], v[240:241], v[34:35] op_sel_hi:[0,1]
	s_waitcnt lgkmcnt(8)
	v_pk_add_f32 v[34:35], v[240:241], v[40:41] op_sel_hi:[0,1]
	s_waitcnt lgkmcnt(6)
	v_pk_add_f32 v[40:41], v[240:241], v[42:43] op_sel_hi:[0,1]
	s_waitcnt lgkmcnt(4)
	v_pk_add_f32 v[42:43], v[240:241], v[44:45] op_sel_hi:[0,1]
	s_waitcnt lgkmcnt(3)
	v_pk_add_f32 v[44:45], v[240:241], v[46:47] op_sel_hi:[0,1]
	s_waitcnt lgkmcnt(2)
	v_pk_add_f32 v[46:47], v[240:241], v[48:49] op_sel_hi:[0,1]
	s_waitcnt lgkmcnt(1)
	v_pk_add_f32 v[48:49], v[240:241], v[50:51] op_sel_hi:[0,1]
	s_waitcnt lgkmcnt(0)
; template <int D> DI size_t attn_vidx(int bh, int s, int d) {
;   const int r = s % D, l = s / D;
;   return ((size_t)((bh * D + r) * (128 / D) + (l >> 4)) * 64 + d) * 16 + (l & 15);
; }
; DI void inproj_epilogue(const Params& p, const char* smem, const int m0, const int n0) {
;     ...
;     const int cc0 = n0 - 2048;
; #pragma unroll 2
;     for (int i = 0; i < 8; ++i) {
;       const int q = threadIdx.x + NT * i, col = q & 127, cidx = q >> 7;
;       const float bias = p.b_in[n0 + col];
;       const int cc = cc0 + col, bh = bbase + (cc >> 6), d = cc & 63;
;     ...
;       V_CHUNK(1, vT);
;       V_CHUNK(4, vT4);
;       V_CHUNK(16, vT16);
	v_pk_add_f32 v[50:51], v[240:241], v[52:53] op_sel_hi:[0,1]
	v_cvt_pk_bf16_f32 v8, v8, v9
	v_cvt_pk_bf16_f32 v9, v10, v11
	v_cvt_pk_bf16_f32 v10, v28, v29
	v_cvt_pk_bf16_f32 v11, v30, v31
	v_cvt_pk_bf16_f32 v28, v32, v33
	v_cvt_pk_bf16_f32 v29, v34, v35
	v_cvt_pk_bf16_f32 v30, v40, v41
	v_cvt_pk_bf16_f32 v31, v42, v43
	v_cvt_pk_bf16_f32 v32, v44, v45
	v_cvt_pk_bf16_f32 v33, v46, v47
	v_cvt_pk_bf16_f32 v34, v48, v49
	v_cvt_pk_bf16_f32 v35, v50, v51
	global_store_dwordx4 v[54:55], v[8:11], off
	global_store_dwordx4 v[56:57], v[28:31], off
	global_store_dwordx4 v[14:15], v[32:35], off
	s_nop 0
	v_mad_u32_u24 v40, v63, s41, v168
	v_mad_u32_u24 v31, v64, s41, v168
	v_mad_u32_u24 v33, v65, s41, v168
	v_mad_u32_u24 v35, v66, s41, v168
	v_mad_u32_u24 v41, v67, s41, v168
	v_and_b32_e32 v42, 0x180, v62
	v_or_b32_e32 v43, s0, v69
	ds_read2_b32 v[8:9], v59 offset0:8 offset1:140
	ds_read2_b32 v[10:11], v60 offset0:16 offset1:148
	ds_read2_b32 v[14:15], v61 offset0:24 offset1:156
	v_lshlrev_b64 v[28:29], 11, v[36:37]
	ds_read_b32 v30, v40
	ds_read_b32 v31, v31
	ds_read_b32 v32, v40 offset:4224
	ds_read_b32 v33, v33
	ds_read_b32 v34, v40 offset:8448
	ds_read_b32 v35, v35
	ds_read_b32 v37, v41
	ds_read_b32 v36, v40 offset:12672
	v_add_u32_e32 v41, v43, v42
	v_lshlrev_b32_e32 v48, 3, v41
	v_lshrrev_b32_e32 v49, 8, v41
	v_or_b32_e32 v40, v42, v69
	v_and_b32_e32 v48, 0x78, v48
	v_or_b32_e32 v49, v49, v7
	v_mad_u32_u24 v46, v40, s41, v168
	v_add_u32_e32 v48, v49, v48
	v_lshl_add_u64 v[28:29], s[20:21], 0, v[28:29]
	v_lshrrev_b32_e32 v52, 3, v41
	ds_read2st64_b32 v[40:41], v46 offset1:33
	ds_read2st64_b32 v[42:43], v46 offset0:66 offset1:99
	ds_read2st64_b32 v[44:45], v46 offset0:132 offset1:165
	ds_read2st64_b32 v[46:47], v46 offset0:198 offset1:231
	v_ashrrev_i32_e32 v49, 31, v48
	v_lshlrev_b64 v[48:49], 11, v[48:49]
	v_lshl_add_u64 v[28:29], v[28:29], 0, v[130:131]
	v_lshlrev_b32_e32 v130, 1, v68
	v_lshl_add_u64 v[48:49], s[24:25], 0, v[48:49]
	v_lshl_add_u64 v[50:51], v[28:29], 0, v[4:5]
	v_lshl_add_u64 v[28:29], v[38:39], 0, v[130:131]
	v_and_b32_e32 v130, 16, v52
	v_lshl_add_u64 v[38:39], v[28:29], 0, v[4:5]
	v_lshl_add_u64 v[28:29], v[48:49], 0, v[130:131]
	v_lshl_add_u64 v[48:49], v[28:29], 0, v[4:5]
	v_add_u32_e32 v25, 0x8400, v25
	v_add_u32_e32 v19, 4, v19
	v_add_u32_e32 v24, 8, v24
	v_add_u32_e32 v23, 0x8400, v23
	v_add_u32_e32 v20, 4, v20
	v_add_u32_e32 v21, 1, v21
	v_add_u32_e32 v22, 16, v22
	s_cmpk_lg_i32 s4, 0x100
	v_pk_add_f32 v[12:13], v[240:241], v[12:13] op_sel_hi:[0,1]
	s_waitcnt lgkmcnt(14)
	v_pk_add_f32 v[28:29], v[240:241], v[8:9] op_sel_hi:[0,1]
	s_waitcnt lgkmcnt(13)
	v_pk_add_f32 v[10:11], v[240:241], v[10:11] op_sel_hi:[0,1]
	s_waitcnt lgkmcnt(12)
	v_pk_add_f32 v[14:15], v[240:241], v[14:15] op_sel_hi:[0,1]
	s_waitcnt lgkmcnt(10)
	v_pk_add_f32 v[30:31], v[240:241], v[30:31] op_sel_hi:[0,1]
	s_waitcnt lgkmcnt(8)
	v_pk_add_f32 v[32:33], v[240:241], v[32:33] op_sel_hi:[0,1]
	s_waitcnt lgkmcnt(6)
	v_pk_add_f32 v[34:35], v[240:241], v[34:35] op_sel_hi:[0,1]
	s_waitcnt lgkmcnt(4)
	v_pk_add_f32 v[36:37], v[240:241], v[36:37] op_sel_hi:[0,1]
	s_waitcnt lgkmcnt(3)
	v_pk_add_f32 v[40:41], v[240:241], v[40:41] op_sel_hi:[0,1]
	s_waitcnt lgkmcnt(2)
	v_pk_add_f32 v[42:43], v[240:241], v[42:43] op_sel_hi:[0,1]
	s_waitcnt lgkmcnt(1)
	v_pk_add_f32 v[44:45], v[240:241], v[44:45] op_sel_hi:[0,1]
	s_waitcnt lgkmcnt(0)
	v_pk_add_f32 v[46:47], v[240:241], v[46:47] op_sel_hi:[0,1]
	v_cvt_pk_bf16_f32 v8, v12, v13
	v_cvt_pk_bf16_f32 v9, v28, v29
	v_cvt_pk_bf16_f32 v10, v10, v11
	v_cvt_pk_bf16_f32 v11, v14, v15
	v_cvt_pk_bf16_f32 v12, v30, v31
	v_cvt_pk_bf16_f32 v13, v32, v33
	v_cvt_pk_bf16_f32 v14, v34, v35
	v_cvt_pk_bf16_f32 v15, v36, v37
	v_cvt_pk_bf16_f32 v28, v40, v41
	v_cvt_pk_bf16_f32 v29, v42, v43
	v_cvt_pk_bf16_f32 v30, v44, v45
	v_cvt_pk_bf16_f32 v31, v46, v47
	global_store_dwordx4 v[50:51], v[8:11], off
	global_store_dwordx4 v[38:39], v[12:15], off
	global_store_dwordx4 v[48:49], v[28:31], off
	s_cbranch_scc1 .LBB0_93
	s_mov_b64 s[84:85], 0
; DI unsigned pack2(float a, float b) { const f32x2 v = {a, b}; const bf16x2_t r = __builtin_convertvector(v, bf16x2_t); return __builtin_bit_cast(unsigned, r); }
; template <int D> DI size_t attn_kidx(int bh, int s, int d) {
;   const int r = s % D, l = s / D;
;   return ((size_t)((bh * D + r) * (128 / D) + (l >> 4)) * 8 + (d >> 3)) * 128 + (l & 15) * 8 + (d & 7);
; }
; DI void inproj_epilogue(const Params& p, const char* smem, const int m0, const int n0) {
;     ...
;   if (n0 < 2048) {
;     const int cc0 = n0 - 1536;
; #pragma unroll 2
;     for (int i = 0; i < 8; ++i) {
;       const int q = threadIdx.x + NT * i, row = q >> 4, ch16 = q & 15;
;       const float4 y0 = *(const float4*)(ct + row * CT_PITCH + 8 * ch16), y1 = *(const float4*)(ct + row * CT_PITCH + 8 * ch16 + 4);
;       const float4 b0 = *(const float4*)(p.b_in + n0 + 8 * ch16), b1 = *(const float4*)(p.b_in + n0 + 8 * ch16 + 4);
;       uint4 r; r.x = pack2(y0.x + b0.x, y0.y + b0.y); r.y = pack2(y0.z + b0.z, y0.w + b0.w); r.z = pack2(y1.x + b1.x, y1.y + b1.y); r.w = pack2(y1.z + b1.z, y1.w + b1.w);
;       const int cc = cc0 + 8 * ch16, bh = bbase + (cc >> 6), d = cc & 63, s = s0 + row;
;       *(uint4*)(kb + attn_kidx<1>(bh, s, d)) = r;
;       *(uint4*)(k4 + attn_kidx<4>(bh, s, d)) = r;
;       *(uint4*)(k16 + attn_kidx<16>(bh, s, d)) = r;
;     }
.LBB0_95:
	s_and_b64 vcc, exec, s[84:85]
	s_cbranch_vccz .LBB0_98
	v_add_u32_e32 v6, s78, v202
	v_add_u32_e32 v4, s0, v178
	v_lshlrev_b32_e32 v7, 1, v6
	s_lshl_b32 s5, s43, 7
	v_and_b32_e32 v10, 0xffffff80, v7
	v_lshrrev_b32_e32 v7, 6, v4
	s_and_b32 s5, s5, 0xfffffc00
	v_or_b32_e32 v7, s5, v7
	v_and_b32_e32 v9, 0x60, v191
	v_add_u32_e32 v11, v7, v9
	v_lshrrev_b32_e32 v7, 4, v4
	v_add_u32_e32 v14, s0, v149
	v_add_u32_e32 v2, s82, v174
	v_or_b32_e32 v13, s5, v7
	v_lshrrev_b32_e32 v7, 6, v14
	v_lshrrev_b32_e32 v3, 6, v2
	v_lshlrev_b32_e32 v2, 4, v2
	s_and_b32 s4, s43, 7
	v_or_b32_e32 v7, s5, v7
	v_and_b32_e32 v9, 0x60, v195
	v_lshlrev_b32_e32 v6, 5, v6
	v_add_u32_e32 v3, s1, v3
	v_and_b32_e32 v8, 0x380, v2
	s_mov_b32 s79, s9
	s_lshl_b32 s1, s4, 9
	s_lshl_b32 s4, s4, 11
	v_add_u32_e32 v15, v7, v9
	v_lshrrev_b32_e32 v7, 4, v14
	v_and_b32_e32 v130, 0x700, v6
	v_or_b32_e32 v9, s5, v176
	v_lshl_or_b32 v5, v3, 7, v176
	v_lshl_add_u64 v[2:3], s[78:79], 2, v[134:135]
	v_or_b32_e32 v12, s4, v192
	v_or_b32_e32 v16, s4, v175
	v_or_b32_e32 v17, s5, v7
	v_lshl_add_u64 v[6:7], v[138:139], 0, v[130:131]
	v_add_u32_e32 v18, v9, v10
	s_mov_b64 s[84:85], 0
	v_lshlrev_b32_e32 v8, 1, v8
	v_mov_b32_e32 v19, v196
	v_mov_b32_e32 v20, v193
	v_mov_b32_e32 v21, v189
	global_load_dwordx4 v[240:243], v[2:3], off offset:512
	global_load_dwordx4 v[244:247], v[2:3], off offset:528
	s_waitcnt vmcnt(0)
.LBB0_97:
	s_nop 0
	s_nop 0
	ds_read_b128 v[30:33], v19
	ds_read_b128 v[34:37], v19 offset:16
	v_lshrrev_b32_e32 v39, 8, v14
	v_add_u32_e32 v38, v10, v17
	v_and_b32_e32 v41, 0x78, v16
	v_add_u32_e32 v40, v10, v15
	v_add_u32_e32 v42, v18, v39
	v_ashrrev_i32_e32 v39, 31, v38
	v_add_u32_e32 v43, s1, v194
	v_lshlrev_b32_e32 v130, 1, v41
	v_ashrrev_i32_e32 v41, 31, v40
	v_lshlrev_b64 v[38:39], 11, v[38:39]
	v_and_b32_e32 v44, 0x78, v43
	v_ashrrev_i32_e32 v43, 31, v42
	v_lshlrev_b64 v[40:41], 11, v[40:41]
	v_lshl_add_u64 v[38:39], s[18:19], 0, v[38:39]
	v_mov_b32_e32 v9, v131
	v_lshlrev_b64 v[42:43], 11, v[42:43]
	v_lshl_add_u64 v[40:41], s[26:27], 0, v[40:41]
	v_lshl_add_u64 v[38:39], v[38:39], 0, v[130:131]
	v_lshlrev_b32_e32 v130, 1, v44
	v_lshl_add_u64 v[42:43], v[6:7], 0, v[42:43]
	v_lshl_add_u64 v[38:39], v[38:39], 0, v[8:9]
	v_lshl_add_u64 v[40:41], v[40:41], 0, v[130:131]
	v_lshl_add_u64 v[42:43], v[42:43], 0, s[84:85]
	v_lshl_add_u64 v[40:41], v[40:41], 0, v[8:9]
	v_and_b32_e32 v44, 0x78, v12
	v_lshlrev_b32_e32 v130, 1, v44
	v_and_b32_e32 v45, 0x78, v21
	v_add_u32_e32 v21, 32, v21
	v_add_u32_e32 v12, 0x200, v12
	v_add_u32_e32 v15, 1, v15
	v_add_u32_e32 v16, 0x200, v16
	v_add_u32_e32 v17, 4, v17
	v_add_u32_e32 v19, 0x8400, v19
	v_add_u32_e32 v14, 64, v14
	s_waitcnt lgkmcnt(1)
	v_pk_add_f32 v[22:23], v[30:31], v[240:241]
	v_pk_add_f32 v[24:25], v[32:33], v[242:243]
	s_waitcnt lgkmcnt(0)
	v_pk_add_f32 v[26:27], v[34:35], v[244:245]
	v_pk_add_f32 v[28:29], v[36:37], v[246:247]
	v_cvt_pk_bf16_f32 v22, v22, v23
	v_cvt_pk_bf16_f32 v23, v24, v25
	v_cvt_pk_bf16_f32 v24, v26, v27
	v_cvt_pk_bf16_f32 v25, v28, v29
	global_store_dwordx4 v[38:39], v[22:25], off
	global_store_dwordx4 v[40:41], v[22:25], off
	global_store_dwordx4 v[42:43], v[22:25], off offset:-8
	s_nop 0
	s_nop 0
	s_nop 0
	ds_read_b128 v[30:33], v20
	ds_read_b128 v[34:37], v20 offset:16
	v_add_u32_e32 v42, s84, v4
	v_add_u32_e32 v38, v10, v13
	v_add_u32_e32 v40, v10, v11
	v_ashrrev_i32_e32 v39, 31, v38
	v_lshrrev_b32_e32 v42, 8, v42
	v_add_u32_e32 v43, s1, v190
	v_ashrrev_i32_e32 v41, 31, v40
	v_lshlrev_b64 v[38:39], 11, v[38:39]
	v_add_u32_e32 v42, v5, v42
	v_and_b32_e32 v46, 0x78, v43
	v_lshlrev_b64 v[40:41], 11, v[40:41]
	v_lshl_add_u64 v[38:39], s[18:19], 0, v[38:39]
	v_ashrrev_i32_e32 v43, 31, v42
	v_lshl_add_u64 v[40:41], s[26:27], 0, v[40:41]
	v_lshlrev_b64 v[42:43], 11, v[42:43]
	s_add_u32 s84, s84, 64
	v_lshl_add_u64 v[38:39], v[38:39], 0, v[130:131]
	v_lshlrev_b32_e32 v130, 1, v46
	v_lshl_add_u64 v[42:43], s[28:29], 0, v[42:43]
	s_addc_u32 s85, s85, 0
	s_addk_i32 s1, 0x80
	v_lshl_add_u64 v[40:41], v[40:41], 0, v[130:131]
	v_lshlrev_b32_e32 v130, 1, v45
	v_add_u32_e32 v11, 1, v11
	v_add_u32_e32 v13, 4, v13
	v_add_u32_e32 v20, 0x8400, v20
	v_lshl_add_u64 v[38:39], v[38:39], 0, v[8:9]
	s_cmpk_eq_i32 s84, 0x100
	v_lshl_add_u64 v[42:43], v[42:43], 0, v[130:131]
	v_lshl_add_u64 v[40:41], v[40:41], 0, v[8:9]
	v_lshl_add_u64 v[42:43], v[42:43], 0, v[8:9]
	s_waitcnt lgkmcnt(1)
	v_pk_add_f32 v[22:23], v[30:31], v[240:241]
	v_pk_add_f32 v[24:25], v[32:33], v[242:243]
	s_waitcnt lgkmcnt(0)
	v_pk_add_f32 v[26:27], v[34:35], v[244:245]
	v_pk_add_f32 v[28:29], v[36:37], v[246:247]
	v_cvt_pk_bf16_f32 v22, v22, v23
	v_cvt_pk_bf16_f32 v23, v24, v25
	v_cvt_pk_bf16_f32 v24, v26, v27
	v_cvt_pk_bf16_f32 v25, v28, v29
	global_store_dwordx4 v[38:39], v[22:25], off
	global_store_dwordx4 v[40:41], v[22:25], off
	global_store_dwordx4 v[42:43], v[22:25], off
	s_cbranch_scc0 .LBB0_97

; #define EV_IDS(t, i0, i1, c0, c1) do { i0 = sel_i[(size_t)(t) * 128 + lane]; i1 = sel_i[(size_t)(t) * 128 + 64 + lane]; \
;                                        c0 = cbuf[(size_t)(t) * 128 + lane]; c1 = cbuf[(size_t)(t) * 128 + 64 + lane]; } while (0)
; DI void ev_load(const unsigned char* __restrict__ vb8, const int id0, const int id1, const int cs, const int lane, uint4 (&v)[16]) {
; #pragma unroll
;   for (int i = 0; i < 16; ++i) {
;     const int id = __shfl(i < 8 ? id0 : id1, (8 * i + (lane >> 3)) & 63, 64);
;     v[i] = *(const uint4*)(vb8 + (size_t)id * 1024 + 128 * cs + 16 * (lane & 7));
;   }
; }
; DI void ev_compute(const uint4 (&v)[16], const float c0, const float c1, u16* __restrict__ yrow, const int lane) {
;   f32x2 acc[8];
; #pragma unroll
;   for (int k = 0; k < 8; ++k) acc[k] = f32x2{0.f, 0.f};
; #pragma unroll
;   for (int i = 0; i < 16; ++i) {
;     const float c = __shfl(i < 8 ? c0 : c1, (8 * i + (lane >> 3)) & 63, 64);
;     const f32x2 cc = f32x2{c, c};
;     f32x2 vf[8];
;     fp8x16_to_f32(v[i], vf);
; #pragma unroll
;     for (int k = 0; k < 8; ++k) acc[k] = __builtin_elementwise_fma(vf[k], cc, acc[k]);
;   }
; DI void phase_ev(const Params& p, const unsigned my_xcc, const unsigned my_rank) {
;     ...
;     for (int k = 0; k < K; k += 2) {
;       ev_load(vb8, b0, b1, cs, lane, vB);
;       const int tA2 = TOK(k + 2); int na0, na1; float nca0, nca1;
;       EV_IDS(tA2, na0, na1, nca0, nca1);
;       ev_compute(vA, ca0, ca1, ybuf + (size_t)tA * 1024 + 128 * cs, lane);
;       ev_load(vb8, na0, na1, cs, lane, vA);
;       const int tB2 = TOK(k + 3); int nb0, nb1; float ncb0, ncb1;
;       EV_IDS(tB2, nb0, nb1, ncb0, ncb1);
;       ev_compute(vB, cb0, cb1, ybuf + (size_t)tB * 1024 + 128 * cs, lane);
;       tA = tA2; a0 = na0; a1 = na1; ca0 = nca0; ca1 = nca1; tB = tB2; b0 = nb0; b1 = nb1; cb0 = ncb0; cb1 = ncb1;
.LBB0_570:
	s_add_i32 s24, s19, -1
	s_min_i32 s0, s24, s41
	s_waitcnt vmcnt(2)
	ds_bpermute_b32 v66, v168, v185
	s_mul_i32 s0, s0, s39
	s_add_i32 s0, s0, s33
	s_lshl_b32 s0, s0, 3
	s_add_i32 s20, s0, s38
	s_ashr_i32 s21, s20, 31
	s_waitcnt lgkmcnt(0)
	s_lshl_b64 s[0:1], s[20:21], 9
	s_add_u32 s100, s26, s0
	s_addc_u32 s101, s27, s1
	s_add_u32 s46, s28, s0
	s_addc_u32 s47, s29, s1
	v_lshl_add_u32 v66, v66, 10, v204
	global_load_dwordx4 v[126:129], v66, s[98:99]
	global_load_dword v157, v174, s[100:101]
	ds_bpermute_b32 v66, v169, v185
	global_load_dword v181, v174, s[46:47]
	s_waitcnt lgkmcnt(0)
	v_lshl_add_u32 v66, v66, 10, v204
	global_load_dwordx4 v[122:125], v66, s[98:99]
	ds_bpermute_b32 v66, v170, v185
	global_load_dword v182, v174, s[46:47] offset:256
	s_waitcnt vmcnt(5)
	ds_bpermute_b32 v158, v168, v155
	v_cvt_pk_f32_fp8_e32 v[160:161], v62
	s_waitcnt lgkmcnt(1)
	v_lshl_add_u32 v66, v66, 10, v204
	global_load_dwordx4 v[118:121], v66, s[98:99]
	ds_bpermute_b32 v66, v171, v185
	global_load_dword v156, v174, s[100:101] offset:256
	v_cvt_pk_f32_fp8_sdwa v[162:163], v62 src0_sel:WORD_1
	v_cvt_pk_f32_fp8_e32 v[164:165], v63
	v_cvt_pk_f32_fp8_sdwa v[62:63], v63 src0_sel:WORD_1
	s_waitcnt lgkmcnt(0)
	v_lshl_add_u32 v66, v66, 10, v204
	global_load_dwordx4 v[114:117], v66, s[98:99]
	ds_bpermute_b32 v66, v172, v185
	v_cvt_pk_f32_fp8_sdwa v[186:187], v64 src0_sel:WORD_1
	v_cvt_pk_f32_fp8_e32 v[188:189], v65
	v_pk_fma_f32 v[160:161], v[160:161], v[158:159], 0 op_sel_hi:[1,0,0]
	v_pk_fma_f32 v[162:163], v[162:163], v[158:159], 0 op_sel_hi:[1,0,0]
	s_waitcnt lgkmcnt(0)
	v_lshl_add_u32 v66, v66, 10, v204
	global_load_dwordx4 v[110:113], v66, s[98:99]
	ds_bpermute_b32 v66, v173, v185
	v_pk_fma_f32 v[164:165], v[164:165], v[158:159], 0 op_sel_hi:[1,0,0]
	v_pk_fma_f32 v[62:63], v[62:63], v[158:159], 0 op_sel_hi:[1,0,0]
	v_pk_fma_f32 v[186:187], v[186:187], v[158:159], 0 op_sel_hi:[1,0,0]
	v_pk_fma_f32 v[188:189], v[188:189], v[158:159], 0 op_sel_hi:[1,0,0]
	s_waitcnt lgkmcnt(0)
	v_lshl_add_u32 v66, v66, 10, v204
	global_load_dwordx4 v[106:109], v66, s[98:99]
	ds_bpermute_b32 v66, v175, v185
	v_cvt_pk_f32_fp8_e32 v[196:197], v60
	v_cvt_pk_f32_fp8_sdwa v[198:199], v60 src0_sel:WORD_1
	v_cvt_pk_f32_fp8_e32 v[202:203], v61
	v_cvt_pk_f32_fp8_sdwa v[60:61], v61 src0_sel:WORD_1
	s_waitcnt lgkmcnt(0)
	v_lshl_add_u32 v66, v66, 10, v204
	global_load_dwordx4 v[102:105], v66, s[98:99]
	ds_bpermute_b32 v66, v176, v185
	v_cvt_pk_f32_fp8_e32 v[190:191], v58
	v_cvt_pk_f32_fp8_sdwa v[192:193], v58 src0_sel:WORD_1
	v_cvt_pk_f32_fp8_e32 v[194:195], v59
	v_cvt_pk_f32_fp8_sdwa v[58:59], v59 src0_sel:WORD_1
	s_waitcnt lgkmcnt(0)
	v_lshl_add_u32 v66, v66, 10, v204
	global_load_dwordx4 v[98:101], v66, s[98:99]
	ds_bpermute_b32 v66, v168, v184
	s_ashr_i32 s37, s36, 31
	s_lshl_b64 s[34:35], s[36:37], 11
	s_min_i32 s0, s19, s41
	s_mul_i32 s0, s0, s39
	s_waitcnt lgkmcnt(0)
	v_lshl_add_u32 v66, v66, 10, v204
	global_load_dwordx4 v[94:97], v66, s[98:99]
	ds_bpermute_b32 v66, v169, v184
	s_add_i32 s0, s0, s33
	s_lshl_b32 s0, s0, 3
	ds_bpermute_b32 v166, v169, v183
	s_ashr_i32 s31, s30, 31
	s_waitcnt lgkmcnt(1)
	v_lshl_add_u32 v66, v66, 10, v204
	global_load_dwordx4 v[90:93], v66, s[98:99]
	ds_bpermute_b32 v66, v170, v184
	s_lshl_b64 s[30:31], s[30:31], 11
	s_add_i32 s19, s19, 2
	s_mov_b32 s36, s20
	s_waitcnt lgkmcnt(0)
	v_lshl_add_u32 v66, v66, 10, v204
	global_load_dwordx4 v[86:89], v66, s[98:99]
	ds_bpermute_b32 v66, v171, v184
	s_waitcnt lgkmcnt(0)
	v_lshl_add_u32 v66, v66, 10, v204
	global_load_dwordx4 v[82:85], v66, s[98:99]
	ds_bpermute_b32 v66, v172, v184
	s_waitcnt lgkmcnt(0)
	v_lshl_add_u32 v66, v66, 10, v204
	global_load_dwordx4 v[78:81], v66, s[98:99]
	ds_bpermute_b32 v66, v173, v184
	s_waitcnt lgkmcnt(0)
	v_lshl_add_u32 v66, v66, 10, v204
	global_load_dwordx4 v[74:77], v66, s[98:99]
	ds_bpermute_b32 v66, v175, v184
	s_waitcnt lgkmcnt(0)
	v_lshl_add_u32 v66, v66, 10, v204
	global_load_dwordx4 v[70:73], v66, s[98:99]
	ds_bpermute_b32 v66, v176, v184
	v_cvt_pk_f32_fp8_e32 v[184:185], v64
	v_cvt_pk_f32_fp8_sdwa v[64:65], v65 src0_sel:WORD_1
	v_pk_fma_f32 v[184:185], v[184:185], v[158:159], 0 op_sel_hi:[1,0,0]
	v_pk_fma_f32 v[64:65], v[64:65], v[158:159], 0 op_sel_hi:[1,0,0]
	ds_bpermute_b32 v158, v169, v155
	s_waitcnt lgkmcnt(1)
	v_lshl_add_u32 v66, v66, 10, v204
	global_load_dwordx4 v[66:69], v66, s[98:99]
	s_waitcnt lgkmcnt(0)
	v_pk_fma_f32 v[60:61], v[60:61], v[158:159], v[64:65] op_sel_hi:[1,0,1]
	ds_bpermute_b32 v64, v170, v155
	v_pk_fma_f32 v[162:163], v[192:193], v[158:159], v[162:163] op_sel_hi:[1,0,1]
	v_pk_fma_f32 v[164:165], v[194:195], v[158:159], v[164:165] op_sel_hi:[1,0,1]
	v_pk_fma_f32 v[58:59], v[58:59], v[158:159], v[62:63] op_sel_hi:[1,0,1]
	v_pk_fma_f32 v[62:63], v[196:197], v[158:159], v[184:185] op_sel_hi:[1,0,1]
	v_cvt_pk_f32_fp8_e32 v[192:193], v56
	v_cvt_pk_f32_fp8_sdwa v[194:195], v56 src0_sel:WORD_1
	v_cvt_pk_f32_fp8_e32 v[196:197], v57
	v_cvt_pk_f32_fp8_sdwa v[56:57], v57 src0_sel:WORD_1
	v_pk_fma_f32 v[160:161], v[190:191], v[158:159], v[160:161] op_sel_hi:[1,0,1]
	v_pk_fma_f32 v[184:185], v[198:199], v[158:159], v[186:187] op_sel_hi:[1,0,1]
	v_pk_fma_f32 v[186:187], v[202:203], v[158:159], v[188:189] op_sel_hi:[1,0,1]
	v_cvt_pk_f32_fp8_e32 v[158:159], v54
	v_cvt_pk_f32_fp8_sdwa v[188:189], v54 src0_sel:WORD_1
	v_cvt_pk_f32_fp8_e32 v[190:191], v55
	v_cvt_pk_f32_fp8_sdwa v[54:55], v55 src0_sel:WORD_1
	s_waitcnt lgkmcnt(0)
; DI void ev_compute(const uint4 (&v)[16], const float c0, const float c1, u16* __restrict__ yrow, const int lane) {
;   f32x2 acc[8];
; #pragma unroll
;   for (int k = 0; k < 8; ++k) acc[k] = f32x2{0.f, 0.f};
; #pragma unroll
;   for (int i = 0; i < 16; ++i) {
;     const float c = __shfl(i < 8 ? c0 : c1, (8 * i + (lane >> 3)) & 63, 64);
;     const f32x2 cc = f32x2{c, c};
;     f32x2 vf[8];
;     fp8x16_to_f32(v[i], vf);
; #pragma unroll
;     for (int k = 0; k < 8; ++k) acc[k] = __builtin_elementwise_fma(vf[k], cc, acc[k]);
;   }
	v_pk_fma_f32 v[56:57], v[56:57], v[64:65], v[60:61] op_sel_hi:[1,0,1]
	ds_bpermute_b32 v60, v171, v155
	v_pk_fma_f32 v[158:159], v[158:159], v[64:65], v[160:161] op_sel_hi:[1,0,1]
	v_pk_fma_f32 v[160:161], v[188:189], v[64:65], v[162:163] op_sel_hi:[1,0,1]
	v_pk_fma_f32 v[162:163], v[190:191], v[64:65], v[164:165] op_sel_hi:[1,0,1]
	v_pk_fma_f32 v[54:55], v[54:55], v[64:65], v[58:59] op_sel_hi:[1,0,1]
	v_pk_fma_f32 v[58:59], v[192:193], v[64:65], v[62:63] op_sel_hi:[1,0,1]
	v_cvt_pk_f32_fp8_e32 v[188:189], v52
	v_cvt_pk_f32_fp8_sdwa v[190:191], v52 src0_sel:WORD_1
	v_cvt_pk_f32_fp8_e32 v[192:193], v53
	v_cvt_pk_f32_fp8_sdwa v[52:53], v53 src0_sel:WORD_1
	v_pk_fma_f32 v[62:63], v[194:195], v[64:65], v[184:185] op_sel_hi:[1,0,1]
	v_pk_fma_f32 v[164:165], v[196:197], v[64:65], v[186:187] op_sel_hi:[1,0,1]
	v_cvt_pk_f32_fp8_e32 v[64:65], v50
	v_cvt_pk_f32_fp8_sdwa v[184:185], v50 src0_sel:WORD_1
	v_cvt_pk_f32_fp8_e32 v[186:187], v51
	v_cvt_pk_f32_fp8_sdwa v[50:51], v51 src0_sel:WORD_1
	s_waitcnt lgkmcnt(0)
	v_pk_fma_f32 v[52:53], v[52:53], v[60:61], v[56:57] op_sel_hi:[1,0,1]
	ds_bpermute_b32 v56, v172, v155
	v_pk_fma_f32 v[64:65], v[64:65], v[60:61], v[158:159] op_sel_hi:[1,0,1]
	v_pk_fma_f32 v[158:159], v[184:185], v[60:61], v[160:161] op_sel_hi:[1,0,1]
	v_pk_fma_f32 v[160:161], v[186:187], v[60:61], v[162:163] op_sel_hi:[1,0,1]
	v_pk_fma_f32 v[50:51], v[50:51], v[60:61], v[54:55] op_sel_hi:[1,0,1]
	v_pk_fma_f32 v[54:55], v[188:189], v[60:61], v[58:59] op_sel_hi:[1,0,1]
	v_cvt_pk_f32_fp8_e32 v[184:185], v48
	v_cvt_pk_f32_fp8_sdwa v[186:187], v48 src0_sel:WORD_1
	v_cvt_pk_f32_fp8_e32 v[188:189], v49
	v_cvt_pk_f32_fp8_sdwa v[48:49], v49 src0_sel:WORD_1
	v_pk_fma_f32 v[58:59], v[190:191], v[60:61], v[62:63] op_sel_hi:[1,0,1]
	v_pk_fma_f32 v[62:63], v[192:193], v[60:61], v[164:165] op_sel_hi:[1,0,1]
	v_cvt_pk_f32_fp8_e32 v[60:61], v46
	v_cvt_pk_f32_fp8_sdwa v[162:163], v46 src0_sel:WORD_1
	v_cvt_pk_f32_fp8_e32 v[164:165], v47
	v_cvt_pk_f32_fp8_sdwa v[46:47], v47 src0_sel:WORD_1
	s_waitcnt lgkmcnt(0)
	v_pk_fma_f32 v[48:49], v[48:49], v[56:57], v[52:53] op_sel_hi:[1,0,1]
	ds_bpermute_b32 v52, v173, v155
	v_pk_fma_f32 v[60:61], v[60:61], v[56:57], v[64:65] op_sel_hi:[1,0,1]
	v_pk_fma_f32 v[64:65], v[162:163], v[56:57], v[158:159] op_sel_hi:[1,0,1]
	v_pk_fma_f32 v[158:159], v[164:165], v[56:57], v[160:161] op_sel_hi:[1,0,1]
	v_pk_fma_f32 v[46:47], v[46:47], v[56:57], v[50:51] op_sel_hi:[1,0,1]
	v_pk_fma_f32 v[50:51], v[184:185], v[56:57], v[54:55] op_sel_hi:[1,0,1]
	v_cvt_pk_f32_fp8_e32 v[162:163], v44
	v_cvt_pk_f32_fp8_sdwa v[164:165], v44 src0_sel:WORD_1
	v_cvt_pk_f32_fp8_e32 v[184:185], v45
	v_cvt_pk_f32_fp8_sdwa v[44:45], v45 src0_sel:WORD_1
	v_pk_fma_f32 v[54:55], v[186:187], v[56:57], v[58:59] op_sel_hi:[1,0,1]
	v_pk_fma_f32 v[58:59], v[188:189], v[56:57], v[62:63] op_sel_hi:[1,0,1]
	v_cvt_pk_f32_fp8_e32 v[56:57], v42
	v_cvt_pk_f32_fp8_sdwa v[62:63], v42 src0_sel:WORD_1
	v_cvt_pk_f32_fp8_e32 v[160:161], v43
	v_cvt_pk_f32_fp8_sdwa v[42:43], v43 src0_sel:WORD_1
	s_waitcnt lgkmcnt(0)
	v_pk_fma_f32 v[44:45], v[44:45], v[52:53], v[48:49] op_sel_hi:[1,0,1]
	ds_bpermute_b32 v48, v175, v155
	v_pk_fma_f32 v[56:57], v[56:57], v[52:53], v[60:61] op_sel_hi:[1,0,1]
	v_pk_fma_f32 v[60:61], v[62:63], v[52:53], v[64:65] op_sel_hi:[1,0,1]
	v_pk_fma_f32 v[62:63], v[160:161], v[52:53], v[158:159] op_sel_hi:[1,0,1]
	v_pk_fma_f32 v[42:43], v[42:43], v[52:53], v[46:47] op_sel_hi:[1,0,1]
	v_pk_fma_f32 v[46:47], v[162:163], v[52:53], v[50:51] op_sel_hi:[1,0,1]
	v_cvt_pk_f32_fp8_e32 v[158:159], v40
	v_cvt_pk_f32_fp8_sdwa v[160:161], v40 src0_sel:WORD_1
	v_cvt_pk_f32_fp8_e32 v[162:163], v41
	v_cvt_pk_f32_fp8_sdwa v[40:41], v41 src0_sel:WORD_1
	v_pk_fma_f32 v[50:51], v[164:165], v[52:53], v[54:55] op_sel_hi:[1,0,1]
	v_pk_fma_f32 v[54:55], v[184:185], v[52:53], v[58:59] op_sel_hi:[1,0,1]
	v_cvt_pk_f32_fp8_e32 v[52:53], v38
	v_cvt_pk_f32_fp8_sdwa v[58:59], v38 src0_sel:WORD_1
	v_cvt_pk_f32_fp8_e32 v[64:65], v39
	v_cvt_pk_f32_fp8_sdwa v[38:39], v39 src0_sel:WORD_1
	s_waitcnt lgkmcnt(0)
	v_pk_fma_f32 v[40:41], v[40:41], v[48:49], v[44:45] op_sel_hi:[1,0,1]
	ds_bpermute_b32 v44, v176, v155
	v_pk_fma_f32 v[52:53], v[52:53], v[48:49], v[56:57] op_sel_hi:[1,0,1]
	v_pk_fma_f32 v[56:57], v[58:59], v[48:49], v[60:61] op_sel_hi:[1,0,1]
	v_pk_fma_f32 v[58:59], v[64:65], v[48:49], v[62:63] op_sel_hi:[1,0,1]
	v_pk_fma_f32 v[38:39], v[38:39], v[48:49], v[42:43] op_sel_hi:[1,0,1]
	v_pk_fma_f32 v[42:43], v[158:159], v[48:49], v[46:47] op_sel_hi:[1,0,1]
	v_cvt_pk_f32_fp8_e32 v[62:63], v36
	v_cvt_pk_f32_fp8_sdwa v[64:65], v36 src0_sel:WORD_1
	v_cvt_pk_f32_fp8_e32 v[158:159], v37
	v_cvt_pk_f32_fp8_sdwa v[36:37], v37 src0_sel:WORD_1
	v_pk_fma_f32 v[46:47], v[160:161], v[48:49], v[50:51] op_sel_hi:[1,0,1]
	v_pk_fma_f32 v[50:51], v[162:163], v[48:49], v[54:55] op_sel_hi:[1,0,1]
	v_cvt_pk_f32_fp8_e32 v[48:49], v34
	v_cvt_pk_f32_fp8_sdwa v[54:55], v34 src0_sel:WORD_1
	v_cvt_pk_f32_fp8_e32 v[60:61], v35
	v_cvt_pk_f32_fp8_sdwa v[34:35], v35 src0_sel:WORD_1
	s_waitcnt lgkmcnt(0)
	v_pk_fma_f32 v[36:37], v[36:37], v[44:45], v[40:41] op_sel_hi:[1,0,1]
	ds_bpermute_b32 v40, v168, v154
	v_pk_fma_f32 v[48:49], v[48:49], v[44:45], v[52:53] op_sel_hi:[1,0,1]
	v_pk_fma_f32 v[52:53], v[54:55], v[44:45], v[56:57] op_sel_hi:[1,0,1]
	v_pk_fma_f32 v[54:55], v[60:61], v[44:45], v[58:59] op_sel_hi:[1,0,1]
	v_pk_fma_f32 v[34:35], v[34:35], v[44:45], v[38:39] op_sel_hi:[1,0,1]
	v_pk_fma_f32 v[38:39], v[62:63], v[44:45], v[42:43] op_sel_hi:[1,0,1]
	v_cvt_pk_f32_fp8_e32 v[58:59], v32
	v_cvt_pk_f32_fp8_sdwa v[60:61], v32 src0_sel:WORD_1
	v_cvt_pk_f32_fp8_e32 v[62:63], v33
	v_cvt_pk_f32_fp8_sdwa v[32:33], v33 src0_sel:WORD_1
	v_pk_fma_f32 v[42:43], v[64:65], v[44:45], v[46:47] op_sel_hi:[1,0,1]
	v_pk_fma_f32 v[46:47], v[158:159], v[44:45], v[50:51] op_sel_hi:[1,0,1]
	v_cvt_pk_f32_fp8_e32 v[44:45], v30
	v_cvt_pk_f32_fp8_sdwa v[50:51], v30 src0_sel:WORD_1
	v_cvt_pk_f32_fp8_e32 v[56:57], v31
	v_cvt_pk_f32_fp8_sdwa v[30:31], v31 src0_sel:WORD_1
	s_waitcnt lgkmcnt(0)
; DI void ev_compute(const uint4 (&v)[16], const float c0, const float c1, u16* __restrict__ yrow, const int lane) {
;   f32x2 acc[8];
; #pragma unroll
;   for (int k = 0; k < 8; ++k) acc[k] = f32x2{0.f, 0.f};
; #pragma unroll
;   for (int i = 0; i < 16; ++i) {
;     const float c = __shfl(i < 8 ? c0 : c1, (8 * i + (lane >> 3)) & 63, 64);
;     const f32x2 cc = f32x2{c, c};
;     f32x2 vf[8];
;     fp8x16_to_f32(v[i], vf);
; #pragma unroll
;     for (int k = 0; k < 8; ++k) acc[k] = __builtin_elementwise_fma(vf[k], cc, acc[k]);
;   }
	v_pk_fma_f32 v[32:33], v[32:33], v[40:41], v[36:37] op_sel_hi:[1,0,1]
	ds_bpermute_b32 v36, v169, v154
	v_pk_fma_f32 v[44:45], v[44:45], v[40:41], v[48:49] op_sel_hi:[1,0,1]
	v_pk_fma_f32 v[48:49], v[50:51], v[40:41], v[52:53] op_sel_hi:[1,0,1]
	v_pk_fma_f32 v[50:51], v[56:57], v[40:41], v[54:55] op_sel_hi:[1,0,1]
	v_pk_fma_f32 v[30:31], v[30:31], v[40:41], v[34:35] op_sel_hi:[1,0,1]
	v_pk_fma_f32 v[34:35], v[58:59], v[40:41], v[38:39] op_sel_hi:[1,0,1]
	v_cvt_pk_f32_fp8_e32 v[54:55], v28
	v_cvt_pk_f32_fp8_sdwa v[56:57], v28 src0_sel:WORD_1
	v_cvt_pk_f32_fp8_e32 v[58:59], v29
	v_cvt_pk_f32_fp8_sdwa v[28:29], v29 src0_sel:WORD_1
	v_pk_fma_f32 v[38:39], v[60:61], v[40:41], v[42:43] op_sel_hi:[1,0,1]
	v_pk_fma_f32 v[42:43], v[62:63], v[40:41], v[46:47] op_sel_hi:[1,0,1]
	v_cvt_pk_f32_fp8_e32 v[40:41], v26
	v_cvt_pk_f32_fp8_sdwa v[46:47], v26 src0_sel:WORD_1
	v_cvt_pk_f32_fp8_e32 v[52:53], v27
	v_cvt_pk_f32_fp8_sdwa v[26:27], v27 src0_sel:WORD_1
	s_waitcnt lgkmcnt(0)
	v_pk_fma_f32 v[28:29], v[28:29], v[36:37], v[32:33] op_sel_hi:[1,0,1]
	ds_bpermute_b32 v32, v170, v154
	v_pk_fma_f32 v[40:41], v[40:41], v[36:37], v[44:45] op_sel_hi:[1,0,1]
	v_pk_fma_f32 v[44:45], v[46:47], v[36:37], v[48:49] op_sel_hi:[1,0,1]
	v_pk_fma_f32 v[46:47], v[52:53], v[36:37], v[50:51] op_sel_hi:[1,0,1]
	v_pk_fma_f32 v[26:27], v[26:27], v[36:37], v[30:31] op_sel_hi:[1,0,1]
	v_pk_fma_f32 v[30:31], v[54:55], v[36:37], v[34:35] op_sel_hi:[1,0,1]
	v_cvt_pk_f32_fp8_e32 v[50:51], v24
	v_cvt_pk_f32_fp8_sdwa v[52:53], v24 src0_sel:WORD_1
	v_cvt_pk_f32_fp8_e32 v[54:55], v25
	v_cvt_pk_f32_fp8_sdwa v[24:25], v25 src0_sel:WORD_1
	v_pk_fma_f32 v[34:35], v[56:57], v[36:37], v[38:39] op_sel_hi:[1,0,1]
	v_pk_fma_f32 v[38:39], v[58:59], v[36:37], v[42:43] op_sel_hi:[1,0,1]
	v_cvt_pk_f32_fp8_e32 v[36:37], v22
	v_cvt_pk_f32_fp8_sdwa v[42:43], v22 src0_sel:WORD_1
	v_cvt_pk_f32_fp8_e32 v[48:49], v23
	v_cvt_pk_f32_fp8_sdwa v[22:23], v23 src0_sel:WORD_1
	s_waitcnt lgkmcnt(0)
	v_pk_fma_f32 v[24:25], v[24:25], v[32:33], v[28:29] op_sel_hi:[1,0,1]
	ds_bpermute_b32 v28, v171, v154
	v_pk_fma_f32 v[36:37], v[36:37], v[32:33], v[40:41] op_sel_hi:[1,0,1]
	v_pk_fma_f32 v[40:41], v[42:43], v[32:33], v[44:45] op_sel_hi:[1,0,1]
	v_pk_fma_f32 v[42:43], v[48:49], v[32:33], v[46:47] op_sel_hi:[1,0,1]
	v_pk_fma_f32 v[22:23], v[22:23], v[32:33], v[26:27] op_sel_hi:[1,0,1]
	v_pk_fma_f32 v[26:27], v[50:51], v[32:33], v[30:31] op_sel_hi:[1,0,1]
	v_cvt_pk_f32_fp8_e32 v[46:47], v20
	v_cvt_pk_f32_fp8_sdwa v[48:49], v20 src0_sel:WORD_1
	v_cvt_pk_f32_fp8_e32 v[50:51], v21
	v_cvt_pk_f32_fp8_sdwa v[20:21], v21 src0_sel:WORD_1
	v_pk_fma_f32 v[30:31], v[52:53], v[32:33], v[34:35] op_sel_hi:[1,0,1]
	v_pk_fma_f32 v[34:35], v[54:55], v[32:33], v[38:39] op_sel_hi:[1,0,1]
	v_cvt_pk_f32_fp8_e32 v[32:33], v18
	v_cvt_pk_f32_fp8_sdwa v[38:39], v18 src0_sel:WORD_1
	v_cvt_pk_f32_fp8_e32 v[44:45], v19
	v_cvt_pk_f32_fp8_sdwa v[18:19], v19 src0_sel:WORD_1
	s_waitcnt lgkmcnt(0)
	v_pk_fma_f32 v[20:21], v[20:21], v[28:29], v[24:25] op_sel_hi:[1,0,1]
	ds_bpermute_b32 v24, v172, v154
	v_pk_fma_f32 v[32:33], v[32:33], v[28:29], v[36:37] op_sel_hi:[1,0,1]
	v_pk_fma_f32 v[36:37], v[38:39], v[28:29], v[40:41] op_sel_hi:[1,0,1]
	v_pk_fma_f32 v[38:39], v[44:45], v[28:29], v[42:43] op_sel_hi:[1,0,1]
	v_pk_fma_f32 v[18:19], v[18:19], v[28:29], v[22:23] op_sel_hi:[1,0,1]
	v_pk_fma_f32 v[22:23], v[46:47], v[28:29], v[26:27] op_sel_hi:[1,0,1]
	v_cvt_pk_f32_fp8_e32 v[42:43], v16
	v_cvt_pk_f32_fp8_sdwa v[44:45], v16 src0_sel:WORD_1
	v_cvt_pk_f32_fp8_e32 v[46:47], v17
	v_cvt_pk_f32_fp8_sdwa v[16:17], v17 src0_sel:WORD_1
	v_pk_fma_f32 v[26:27], v[48:49], v[28:29], v[30:31] op_sel_hi:[1,0,1]
	v_pk_fma_f32 v[30:31], v[50:51], v[28:29], v[34:35] op_sel_hi:[1,0,1]
	v_cvt_pk_f32_fp8_e32 v[28:29], v14
	v_cvt_pk_f32_fp8_sdwa v[34:35], v14 src0_sel:WORD_1
	v_cvt_pk_f32_fp8_e32 v[40:41], v15
	v_cvt_pk_f32_fp8_sdwa v[14:15], v15 src0_sel:WORD_1
	s_waitcnt lgkmcnt(0)
	v_pk_fma_f32 v[16:17], v[16:17], v[24:25], v[20:21] op_sel_hi:[1,0,1]
	ds_bpermute_b32 v20, v173, v154
	v_pk_fma_f32 v[28:29], v[28:29], v[24:25], v[32:33] op_sel_hi:[1,0,1]
	v_pk_fma_f32 v[32:33], v[34:35], v[24:25], v[36:37] op_sel_hi:[1,0,1]
	v_pk_fma_f32 v[34:35], v[40:41], v[24:25], v[38:39] op_sel_hi:[1,0,1]
	v_pk_fma_f32 v[14:15], v[14:15], v[24:25], v[18:19] op_sel_hi:[1,0,1]
	v_pk_fma_f32 v[18:19], v[42:43], v[24:25], v[22:23] op_sel_hi:[1,0,1]
	v_cvt_pk_f32_fp8_e32 v[38:39], v12
	v_cvt_pk_f32_fp8_sdwa v[40:41], v12 src0_sel:WORD_1
	v_cvt_pk_f32_fp8_e32 v[42:43], v13
	v_cvt_pk_f32_fp8_sdwa v[12:13], v13 src0_sel:WORD_1
	v_pk_fma_f32 v[22:23], v[44:45], v[24:25], v[26:27] op_sel_hi:[1,0,1]
	v_pk_fma_f32 v[26:27], v[46:47], v[24:25], v[30:31] op_sel_hi:[1,0,1]
	v_cvt_pk_f32_fp8_e32 v[24:25], v10
	v_cvt_pk_f32_fp8_sdwa v[30:31], v10 src0_sel:WORD_1
	v_cvt_pk_f32_fp8_e32 v[36:37], v11
	v_cvt_pk_f32_fp8_sdwa v[10:11], v11 src0_sel:WORD_1
	s_waitcnt lgkmcnt(0)
	v_pk_fma_f32 v[12:13], v[12:13], v[20:21], v[16:17] op_sel_hi:[1,0,1]
	ds_bpermute_b32 v16, v175, v154
	v_pk_fma_f32 v[24:25], v[24:25], v[20:21], v[28:29] op_sel_hi:[1,0,1]
	v_pk_fma_f32 v[28:29], v[30:31], v[20:21], v[32:33] op_sel_hi:[1,0,1]
	v_pk_fma_f32 v[30:31], v[36:37], v[20:21], v[34:35] op_sel_hi:[1,0,1]
	v_pk_fma_f32 v[10:11], v[10:11], v[20:21], v[14:15] op_sel_hi:[1,0,1]
	v_pk_fma_f32 v[14:15], v[38:39], v[20:21], v[18:19] op_sel_hi:[1,0,1]
	v_cvt_pk_f32_fp8_e32 v[34:35], v8
	v_cvt_pk_f32_fp8_sdwa v[36:37], v8 src0_sel:WORD_1
	v_cvt_pk_f32_fp8_e32 v[38:39], v9
	v_cvt_pk_f32_fp8_sdwa v[8:9], v9 src0_sel:WORD_1
	v_pk_fma_f32 v[18:19], v[40:41], v[20:21], v[22:23] op_sel_hi:[1,0,1]
	v_pk_fma_f32 v[22:23], v[42:43], v[20:21], v[26:27] op_sel_hi:[1,0,1]
	v_cvt_pk_f32_fp8_e32 v[20:21], v6
	v_cvt_pk_f32_fp8_sdwa v[26:27], v6 src0_sel:WORD_1
	v_cvt_pk_f32_fp8_e32 v[32:33], v7
	v_cvt_pk_f32_fp8_sdwa v[6:7], v7 src0_sel:WORD_1
	s_waitcnt lgkmcnt(0)
; DI unsigned pack2(float a, float b) { const f32x2 v = {a, b}; const bf16x2_t r = __builtin_convertvector(v, bf16x2_t); return __builtin_bit_cast(unsigned, r); }
; DI void ev_load(const unsigned char* __restrict__ vb8, const int id0, const int id1, const int cs, const int lane, uint4 (&v)[16]) {
; #pragma unroll
;   for (int i = 0; i < 16; ++i) {
;     const int id = __shfl(i < 8 ? id0 : id1, (8 * i + (lane >> 3)) & 63, 64);
;     v[i] = *(const uint4*)(vb8 + (size_t)id * 1024 + 128 * cs + 16 * (lane & 7));
;   }
; }
; DI void ev_compute(const uint4 (&v)[16], const float c0, const float c1, u16* __restrict__ yrow, const int lane) {
;     ...
;   float a[16];
; #pragma unroll
;   for (int k = 0; k < 8; ++k) { a[2 * k] = acc[k][0]; a[2 * k + 1] = acc[k][1]; }
;   float q8[8], q4[4], q2[2];
;   const bool b5 = lane & 32, b4 = lane & 16, b3 = lane & 8;
; #pragma unroll
;   for (int j = 0; j < 8; ++j) { const float keep = b5 ? a[8 + j] : a[j], send = b5 ? a[j] : a[8 + j]; q8[j] = keep + __shfl_xor(send, 32, 64); }
; #pragma unroll
;   for (int j = 0; j < 4; ++j) { const float keep = b4 ? q8[4 + j] : q8[j], send = b4 ? q8[j] : q8[4 + j]; q4[j] = keep + __shfl_xor(send, 16, 64); }
; #pragma unroll
;   for (int j = 0; j < 2; ++j) { const float keep = b3 ? q4[2 + j] : q4[j], send = b3 ? q4[j] : q4[2 + j]; q2[j] = keep + __shfl_xor(send, 8, 64); }
;   *(unsigned*)(yrow + 16 * (lane & 7) + 2 * (lane >> 3)) = pack2(q2[0], q2[1]);
	v_pk_fma_f32 v[8:9], v[8:9], v[16:17], v[12:13] op_sel_hi:[1,0,1]
	ds_bpermute_b32 v12, v176, v154
	v_pk_fma_f32 v[20:21], v[20:21], v[16:17], v[24:25] op_sel_hi:[1,0,1]
	v_pk_fma_f32 v[24:25], v[26:27], v[16:17], v[28:29] op_sel_hi:[1,0,1]
	v_pk_fma_f32 v[26:27], v[32:33], v[16:17], v[30:31] op_sel_hi:[1,0,1]
	v_pk_fma_f32 v[6:7], v[6:7], v[16:17], v[10:11] op_sel_hi:[1,0,1]
	v_pk_fma_f32 v[10:11], v[34:35], v[16:17], v[14:15] op_sel_hi:[1,0,1]
	v_pk_fma_f32 v[14:15], v[36:37], v[16:17], v[18:19] op_sel_hi:[1,0,1]
	v_pk_fma_f32 v[18:19], v[38:39], v[16:17], v[22:23] op_sel_hi:[1,0,1]
	v_cvt_pk_f32_fp8_e32 v[16:17], v2
	v_cvt_pk_f32_fp8_sdwa v[22:23], v2 src0_sel:WORD_1
	v_cvt_pk_f32_fp8_e32 v[28:29], v3
	v_cvt_pk_f32_fp8_sdwa v[2:3], v3 src0_sel:WORD_1
	v_cvt_pk_f32_fp8_e32 v[30:31], v4
	v_cvt_pk_f32_fp8_sdwa v[32:33], v4 src0_sel:WORD_1
	v_cvt_pk_f32_fp8_e32 v[34:35], v5
	v_cvt_pk_f32_fp8_sdwa v[4:5], v5 src0_sel:WORD_1
	s_waitcnt lgkmcnt(0)
	v_pk_fma_f32 v[16:17], v[16:17], v[12:13], v[20:21] op_sel_hi:[1,0,1]
	v_pk_fma_f32 v[2:3], v[2:3], v[12:13], v[6:7] op_sel_hi:[1,0,1]
	v_pk_fma_f32 v[6:7], v[30:31], v[12:13], v[10:11] op_sel_hi:[1,0,1]
	v_pk_fma_f32 v[20:21], v[22:23], v[12:13], v[24:25] op_sel_hi:[1,0,1]
	v_pk_fma_f32 v[22:23], v[28:29], v[12:13], v[26:27] op_sel_hi:[1,0,1]
	v_pk_fma_f32 v[10:11], v[32:33], v[12:13], v[14:15] op_sel_hi:[1,0,1]
	v_pk_fma_f32 v[14:15], v[34:35], v[12:13], v[18:19] op_sel_hi:[1,0,1]
	v_pk_fma_f32 v[4:5], v[4:5], v[12:13], v[8:9] op_sel_hi:[1,0,1]
	v_cndmask_b32_e64 v8, v16, v6, s[6:7]
	v_cndmask_b32_e64 v9, v17, v7, s[6:7]
	ds_bpermute_b32 v8, v177, v8
	ds_bpermute_b32 v9, v177, v9
	v_cndmask_b32_e64 v12, v20, v10, s[6:7]
	v_cndmask_b32_e64 v13, v21, v11, s[6:7]
	v_cndmask_b32_e64 v18, v22, v14, s[6:7]
	v_cndmask_b32_e64 v19, v23, v15, s[6:7]
	v_cndmask_b32_e64 v24, v2, v4, s[6:7]
	v_cndmask_b32_e64 v25, v3, v5, s[6:7]
	ds_bpermute_b32 v12, v177, v12
	ds_bpermute_b32 v13, v177, v13
	ds_bpermute_b32 v18, v177, v18
	ds_bpermute_b32 v19, v177, v19
	ds_bpermute_b32 v24, v177, v24
	ds_bpermute_b32 v25, v177, v25
	v_cndmask_b32_e64 v7, v7, v17, s[6:7]
	v_cndmask_b32_e64 v6, v6, v16, s[6:7]
	s_waitcnt lgkmcnt(6)
	v_pk_add_f32 v[6:7], v[6:7], v[8:9]
	v_cndmask_b32_e64 v9, v11, v21, s[6:7]
	v_cndmask_b32_e64 v8, v10, v20, s[6:7]
	v_cndmask_b32_e64 v11, v15, v23, s[6:7]
	v_cndmask_b32_e64 v10, v14, v22, s[6:7]
	v_cndmask_b32_e64 v3, v5, v3, s[6:7]
	v_cndmask_b32_e64 v2, v4, v2, s[6:7]
	s_waitcnt lgkmcnt(4)
	v_pk_add_f32 v[8:9], v[8:9], v[12:13]
	s_waitcnt lgkmcnt(2)
	v_pk_add_f32 v[10:11], v[10:11], v[18:19]
	s_waitcnt lgkmcnt(0)
	v_pk_add_f32 v[2:3], v[2:3], v[24:25]
	v_cndmask_b32_e64 v4, v6, v10, s[8:9]
	v_cndmask_b32_e64 v12, v10, v6, s[8:9]
	v_cndmask_b32_e64 v5, v7, v11, s[8:9]
	v_cndmask_b32_e64 v6, v8, v2, s[8:9]
	v_cndmask_b32_e64 v10, v2, v8, s[8:9]
	v_cndmask_b32_e64 v2, v9, v3, s[8:9]
	ds_bpermute_b32 v4, v178, v4
	v_cndmask_b32_e64 v13, v11, v7, s[8:9]
	ds_bpermute_b32 v5, v178, v5
	ds_bpermute_b32 v6, v178, v6
	ds_bpermute_b32 v7, v178, v2
	v_cndmask_b32_e64 v11, v3, v9, s[8:9]
	ds_bpermute_b32 v164, v168, v183
	s_waitcnt lgkmcnt(3)
	v_pk_add_f32 v[4:5], v[12:13], v[4:5]
	s_waitcnt vmcnt(19)
	v_cvt_pk_f32_fp8_sdwa v[160:161], v127 src0_sel:WORD_1
	s_waitcnt lgkmcnt(1)
	v_pk_add_f32 v[2:3], v[10:11], v[6:7]
	v_cvt_pk_f32_fp8_e32 v[162:163], v128
	v_cndmask_b32_e64 v6, v4, v2, s[10:11]
	v_cndmask_b32_e64 v8, v2, v4, s[10:11]
	v_cndmask_b32_e64 v2, v5, v3, s[10:11]
	ds_bpermute_b32 v6, v179, v6
	ds_bpermute_b32 v7, v179, v2
	v_cndmask_b32_e64 v9, v3, v5, s[10:11]
	v_cvt_pk_f32_fp8_sdwa v[188:189], v128 src0_sel:WORD_1
	v_cvt_pk_f32_fp8_e32 v[190:191], v129
	v_cvt_pk_f32_fp8_sdwa v[192:193], v129 src0_sel:WORD_1
	s_waitcnt lgkmcnt(0)
	v_pk_add_f32 v[2:3], v[8:9], v[6:7]
	s_waitcnt vmcnt(16)
	v_cvt_pk_f32_fp8_e32 v[194:195], v124
	v_cvt_pk_bf16_f32 v4, v2, v3
	v_lshl_add_u64 v[2:3], v[152:153], 0, s[34:35]
	global_store_dword v[2:3], v4, off
	ds_bpermute_b32 v2, v168, v157
	s_add_i32 s34, s0, s38
	s_ashr_i32 s35, s34, 31
	s_lshl_b64 s[0:1], s[34:35], 9
	s_add_u32 s100, s26, s0
	s_addc_u32 s101, s27, s1
	s_add_u32 s46, s28, s0
	s_addc_u32 s47, s29, s1
	s_waitcnt lgkmcnt(0)
	v_lshl_add_u32 v2, v2, 10, v204
	global_load_dwordx4 v[62:65], v2, s[98:99]
	ds_bpermute_b32 v2, v169, v157
	v_cvt_pk_f32_fp8_sdwa v[196:197], v124 src0_sel:WORD_1
	v_cvt_pk_f32_fp8_e32 v[198:199], v125
	v_cvt_pk_f32_fp8_sdwa v[124:125], v125 src0_sel:WORD_1
	s_waitcnt lgkmcnt(0)
	v_lshl_add_u32 v2, v2, 10, v204
	global_load_dwordx4 v[58:61], v2, s[98:99]
	ds_bpermute_b32 v2, v170, v157
	s_cmp_lt_i32 s24, s40
	s_waitcnt lgkmcnt(0)
	v_lshl_add_u32 v2, v2, 10, v204
	global_load_dwordx4 v[54:57], v2, s[98:99]
	ds_bpermute_b32 v2, v171, v157
	s_waitcnt lgkmcnt(0)
	v_lshl_add_u32 v2, v2, 10, v204
	global_load_dwordx4 v[50:53], v2, s[98:99]
	ds_bpermute_b32 v2, v172, v157
	s_waitcnt lgkmcnt(0)
	v_lshl_add_u32 v2, v2, 10, v204
	global_load_dwordx4 v[46:49], v2, s[98:99]
	ds_bpermute_b32 v2, v173, v157
	s_waitcnt lgkmcnt(0)
	v_lshl_add_u32 v2, v2, 10, v204
	global_load_dwordx4 v[42:45], v2, s[98:99]
	ds_bpermute_b32 v2, v175, v157
	s_waitcnt lgkmcnt(0)
	v_lshl_add_u32 v2, v2, 10, v204
	global_load_dwordx4 v[38:41], v2, s[98:99]
	ds_bpermute_b32 v2, v176, v157
	s_waitcnt lgkmcnt(0)
	v_lshl_add_u32 v2, v2, 10, v204
	global_load_dwordx4 v[34:37], v2, s[98:99]
	s_waitcnt vmcnt(22)
	ds_bpermute_b32 v2, v168, v156
	s_waitcnt lgkmcnt(0)
	v_lshl_add_u32 v2, v2, 10, v204
	global_load_dwordx4 v[30:33], v2, s[98:99]
	ds_bpermute_b32 v2, v169, v156
	s_waitcnt lgkmcnt(0)
	v_lshl_add_u32 v2, v2, 10, v204
	global_load_dwordx4 v[26:29], v2, s[98:99]
	ds_bpermute_b32 v2, v170, v156
	s_waitcnt lgkmcnt(0)
; DI void ev_compute(const uint4 (&v)[16], const float c0, const float c1, u16* __restrict__ yrow, const int lane) {
;   f32x2 acc[8];
; #pragma unroll
;   for (int k = 0; k < 8; ++k) acc[k] = f32x2{0.f, 0.f};
; #pragma unroll
;   for (int i = 0; i < 16; ++i) {
;     const float c = __shfl(i < 8 ? c0 : c1, (8 * i + (lane >> 3)) & 63, 64);
;     const f32x2 cc = f32x2{c, c};
;     f32x2 vf[8];
;     fp8x16_to_f32(v[i], vf);
; #pragma unroll
;     for (int k = 0; k < 8; ++k) acc[k] = __builtin_elementwise_fma(vf[k], cc, acc[k]);
;   }
	v_lshl_add_u32 v2, v2, 10, v204
	global_load_dwordx4 v[22:25], v2, s[98:99]
	ds_bpermute_b32 v2, v171, v156
	s_waitcnt lgkmcnt(0)
	v_lshl_add_u32 v2, v2, 10, v204
	global_load_dwordx4 v[18:21], v2, s[98:99]
	ds_bpermute_b32 v2, v172, v156
	s_waitcnt lgkmcnt(0)
	v_lshl_add_u32 v2, v2, 10, v204
	global_load_dwordx4 v[14:17], v2, s[98:99]
	ds_bpermute_b32 v2, v173, v156
	s_waitcnt lgkmcnt(0)
	v_lshl_add_u32 v2, v2, 10, v204
	global_load_dwordx4 v[10:13], v2, s[98:99]
	ds_bpermute_b32 v2, v175, v156
	s_waitcnt lgkmcnt(0)
	v_lshl_add_u32 v2, v2, 10, v204
	global_load_dwordx4 v[6:9], v2, s[98:99]
	ds_bpermute_b32 v2, v176, v156
	global_load_dword v185, v174, s[100:101]
	s_waitcnt lgkmcnt(0)
	v_lshl_add_u32 v2, v2, 10, v204
	global_load_dwordx4 v[2:5], v2, s[98:99]
	s_nop 0
	global_load_dword v184, v174, s[100:101] offset:256
	global_load_dword v186, v174, s[46:47]
	global_load_dword v187, v174, s[46:47] offset:256
	v_cvt_pk_f32_fp8_e32 v[154:155], v126
	v_cvt_pk_f32_fp8_sdwa v[156:157], v126 src0_sel:WORD_1
	v_cvt_pk_f32_fp8_e32 v[158:159], v127
	v_pk_fma_f32 v[126:127], v[154:155], v[164:165], 0 op_sel_hi:[1,0,0]
	v_pk_fma_f32 v[128:129], v[156:157], v[164:165], 0 op_sel_hi:[1,0,0]
	v_pk_fma_f32 v[154:155], v[158:159], v[164:165], 0 op_sel_hi:[1,0,0]
	v_pk_fma_f32 v[156:157], v[160:161], v[164:165], 0 op_sel_hi:[1,0,0]
	v_pk_fma_f32 v[158:159], v[162:163], v[164:165], 0 op_sel_hi:[1,0,0]
	v_pk_fma_f32 v[160:161], v[188:189], v[164:165], 0 op_sel_hi:[1,0,0]
	v_pk_fma_f32 v[162:163], v[190:191], v[164:165], 0 op_sel_hi:[1,0,0]
	v_pk_fma_f32 v[164:165], v[192:193], v[164:165], 0 op_sel_hi:[1,0,0]
	v_cvt_pk_f32_fp8_e32 v[188:189], v122
	v_cvt_pk_f32_fp8_sdwa v[190:191], v122 src0_sel:WORD_1
	v_cvt_pk_f32_fp8_e32 v[192:193], v123
	v_cvt_pk_f32_fp8_sdwa v[122:123], v123 src0_sel:WORD_1
	v_pk_fma_f32 v[126:127], v[188:189], v[166:167], v[126:127] op_sel_hi:[1,0,1]
	v_pk_fma_f32 v[128:129], v[190:191], v[166:167], v[128:129] op_sel_hi:[1,0,1]
	v_pk_fma_f32 v[154:155], v[192:193], v[166:167], v[154:155] op_sel_hi:[1,0,1]
	v_pk_fma_f32 v[122:123], v[122:123], v[166:167], v[156:157] op_sel_hi:[1,0,1]
	v_pk_fma_f32 v[156:157], v[194:195], v[166:167], v[158:159] op_sel_hi:[1,0,1]
	v_pk_fma_f32 v[158:159], v[196:197], v[166:167], v[160:161] op_sel_hi:[1,0,1]
	v_pk_fma_f32 v[160:161], v[198:199], v[166:167], v[162:163] op_sel_hi:[1,0,1]
	ds_bpermute_b32 v162, v170, v183
	v_cvt_pk_f32_fp8_e32 v[192:193], v120
	v_cvt_pk_f32_fp8_sdwa v[194:195], v120 src0_sel:WORD_1
	v_cvt_pk_f32_fp8_e32 v[196:197], v121
	v_cvt_pk_f32_fp8_sdwa v[120:121], v121 src0_sel:WORD_1
	v_pk_fma_f32 v[124:125], v[124:125], v[166:167], v[164:165] op_sel_hi:[1,0,1]
	v_cvt_pk_f32_fp8_e32 v[164:165], v118
	v_cvt_pk_f32_fp8_sdwa v[188:189], v118 src0_sel:WORD_1
	v_cvt_pk_f32_fp8_e32 v[190:191], v119
	v_cvt_pk_f32_fp8_sdwa v[118:119], v119 src0_sel:WORD_1
	s_waitcnt lgkmcnt(0)
	v_pk_fma_f32 v[120:121], v[120:121], v[162:163], v[124:125] op_sel_hi:[1,0,1]
	ds_bpermute_b32 v124, v171, v183
	v_pk_fma_f32 v[128:129], v[188:189], v[162:163], v[128:129] op_sel_hi:[1,0,1]
	v_pk_fma_f32 v[154:155], v[190:191], v[162:163], v[154:155] op_sel_hi:[1,0,1]
	v_pk_fma_f32 v[118:119], v[118:119], v[162:163], v[122:123] op_sel_hi:[1,0,1]
	v_pk_fma_f32 v[122:123], v[192:193], v[162:163], v[156:157] op_sel_hi:[1,0,1]
	s_waitcnt vmcnt(33)
	v_cvt_pk_f32_fp8_e32 v[188:189], v116
	v_cvt_pk_f32_fp8_sdwa v[190:191], v116 src0_sel:WORD_1
	v_cvt_pk_f32_fp8_e32 v[192:193], v117
	v_cvt_pk_f32_fp8_sdwa v[116:117], v117 src0_sel:WORD_1
	v_pk_fma_f32 v[126:127], v[164:165], v[162:163], v[126:127] op_sel_hi:[1,0,1]
	v_pk_fma_f32 v[156:157], v[194:195], v[162:163], v[158:159] op_sel_hi:[1,0,1]
	v_pk_fma_f32 v[158:159], v[196:197], v[162:163], v[160:161] op_sel_hi:[1,0,1]
	v_cvt_pk_f32_fp8_e32 v[160:161], v114
	v_cvt_pk_f32_fp8_sdwa v[162:163], v114 src0_sel:WORD_1
	v_cvt_pk_f32_fp8_e32 v[164:165], v115
	v_cvt_pk_f32_fp8_sdwa v[114:115], v115 src0_sel:WORD_1
	s_waitcnt lgkmcnt(0)
	v_pk_fma_f32 v[116:117], v[116:117], v[124:125], v[120:121] op_sel_hi:[1,0,1]
	ds_bpermute_b32 v120, v172, v183
	v_pk_fma_f32 v[128:129], v[162:163], v[124:125], v[128:129] op_sel_hi:[1,0,1]
	v_pk_fma_f32 v[154:155], v[164:165], v[124:125], v[154:155] op_sel_hi:[1,0,1]
	v_pk_fma_f32 v[114:115], v[114:115], v[124:125], v[118:119] op_sel_hi:[1,0,1]
	v_pk_fma_f32 v[118:119], v[188:189], v[124:125], v[122:123] op_sel_hi:[1,0,1]
	s_waitcnt vmcnt(32)
	v_cvt_pk_f32_fp8_e32 v[162:163], v112
	v_cvt_pk_f32_fp8_sdwa v[164:165], v112 src0_sel:WORD_1
	v_cvt_pk_f32_fp8_e32 v[188:189], v113
	v_cvt_pk_f32_fp8_sdwa v[112:113], v113 src0_sel:WORD_1
	v_pk_fma_f32 v[126:127], v[160:161], v[124:125], v[126:127] op_sel_hi:[1,0,1]
	v_pk_fma_f32 v[122:123], v[190:191], v[124:125], v[156:157] op_sel_hi:[1,0,1]
	v_pk_fma_f32 v[156:157], v[192:193], v[124:125], v[158:159] op_sel_hi:[1,0,1]
	v_cvt_pk_f32_fp8_e32 v[124:125], v110
	v_cvt_pk_f32_fp8_sdwa v[158:159], v110 src0_sel:WORD_1
	v_cvt_pk_f32_fp8_e32 v[160:161], v111
	v_cvt_pk_f32_fp8_sdwa v[110:111], v111 src0_sel:WORD_1
	s_waitcnt lgkmcnt(0)
	v_pk_fma_f32 v[112:113], v[112:113], v[120:121], v[116:117] op_sel_hi:[1,0,1]
	ds_bpermute_b32 v116, v173, v183
	v_pk_fma_f32 v[124:125], v[124:125], v[120:121], v[126:127] op_sel_hi:[1,0,1]
	v_pk_fma_f32 v[126:127], v[158:159], v[120:121], v[128:129] op_sel_hi:[1,0,1]
	v_pk_fma_f32 v[128:129], v[160:161], v[120:121], v[154:155] op_sel_hi:[1,0,1]
	v_pk_fma_f32 v[110:111], v[110:111], v[120:121], v[114:115] op_sel_hi:[1,0,1]
	v_pk_fma_f32 v[114:115], v[162:163], v[120:121], v[118:119] op_sel_hi:[1,0,1]
	s_waitcnt vmcnt(31)
; DI void ev_compute(const uint4 (&v)[16], const float c0, const float c1, u16* __restrict__ yrow, const int lane) {
;   f32x2 acc[8];
; #pragma unroll
;   for (int k = 0; k < 8; ++k) acc[k] = f32x2{0.f, 0.f};
; #pragma unroll
;   for (int i = 0; i < 16; ++i) {
;     const float c = __shfl(i < 8 ? c0 : c1, (8 * i + (lane >> 3)) & 63, 64);
;     const f32x2 cc = f32x2{c, c};
;     f32x2 vf[8];
;     fp8x16_to_f32(v[i], vf);
; #pragma unroll
;     for (int k = 0; k < 8; ++k) acc[k] = __builtin_elementwise_fma(vf[k], cc, acc[k]);
;   }
	v_cvt_pk_f32_fp8_e32 v[158:159], v108
	v_cvt_pk_f32_fp8_sdwa v[160:161], v108 src0_sel:WORD_1
	v_cvt_pk_f32_fp8_e32 v[162:163], v109
	v_cvt_pk_f32_fp8_sdwa v[108:109], v109 src0_sel:WORD_1
	v_pk_fma_f32 v[118:119], v[164:165], v[120:121], v[122:123] op_sel_hi:[1,0,1]
	v_pk_fma_f32 v[122:123], v[188:189], v[120:121], v[156:157] op_sel_hi:[1,0,1]
	v_cvt_pk_f32_fp8_e32 v[120:121], v106
	v_cvt_pk_f32_fp8_sdwa v[154:155], v106 src0_sel:WORD_1
	v_cvt_pk_f32_fp8_e32 v[156:157], v107
	v_cvt_pk_f32_fp8_sdwa v[106:107], v107 src0_sel:WORD_1
	s_waitcnt lgkmcnt(0)
	v_pk_fma_f32 v[108:109], v[108:109], v[116:117], v[112:113] op_sel_hi:[1,0,1]
	ds_bpermute_b32 v112, v175, v183
	v_pk_fma_f32 v[120:121], v[120:121], v[116:117], v[124:125] op_sel_hi:[1,0,1]
	v_pk_fma_f32 v[124:125], v[154:155], v[116:117], v[126:127] op_sel_hi:[1,0,1]
	v_pk_fma_f32 v[126:127], v[156:157], v[116:117], v[128:129] op_sel_hi:[1,0,1]
	v_pk_fma_f32 v[106:107], v[106:107], v[116:117], v[110:111] op_sel_hi:[1,0,1]
	v_pk_fma_f32 v[110:111], v[158:159], v[116:117], v[114:115] op_sel_hi:[1,0,1]
	s_waitcnt vmcnt(30)
	v_cvt_pk_f32_fp8_e32 v[154:155], v104
	v_cvt_pk_f32_fp8_sdwa v[156:157], v104 src0_sel:WORD_1
	v_cvt_pk_f32_fp8_e32 v[158:159], v105
	v_cvt_pk_f32_fp8_sdwa v[104:105], v105 src0_sel:WORD_1
	v_pk_fma_f32 v[114:115], v[160:161], v[116:117], v[118:119] op_sel_hi:[1,0,1]
	v_pk_fma_f32 v[118:119], v[162:163], v[116:117], v[122:123] op_sel_hi:[1,0,1]
	v_cvt_pk_f32_fp8_e32 v[116:117], v102
	v_cvt_pk_f32_fp8_sdwa v[122:123], v102 src0_sel:WORD_1
	v_cvt_pk_f32_fp8_e32 v[128:129], v103
	v_cvt_pk_f32_fp8_sdwa v[102:103], v103 src0_sel:WORD_1
	s_waitcnt lgkmcnt(0)
	v_pk_fma_f32 v[104:105], v[104:105], v[112:113], v[108:109] op_sel_hi:[1,0,1]
	ds_bpermute_b32 v108, v176, v183
	v_pk_fma_f32 v[116:117], v[116:117], v[112:113], v[120:121] op_sel_hi:[1,0,1]
	v_pk_fma_f32 v[120:121], v[122:123], v[112:113], v[124:125] op_sel_hi:[1,0,1]
	v_pk_fma_f32 v[122:123], v[128:129], v[112:113], v[126:127] op_sel_hi:[1,0,1]
	v_pk_fma_f32 v[102:103], v[102:103], v[112:113], v[106:107] op_sel_hi:[1,0,1]
	v_pk_fma_f32 v[106:107], v[154:155], v[112:113], v[110:111] op_sel_hi:[1,0,1]
	s_waitcnt vmcnt(29)
	v_cvt_pk_f32_fp8_e32 v[126:127], v100
	v_cvt_pk_f32_fp8_sdwa v[128:129], v100 src0_sel:WORD_1
	v_cvt_pk_f32_fp8_e32 v[154:155], v101
	v_cvt_pk_f32_fp8_sdwa v[100:101], v101 src0_sel:WORD_1
	v_pk_fma_f32 v[110:111], v[156:157], v[112:113], v[114:115] op_sel_hi:[1,0,1]
	v_pk_fma_f32 v[114:115], v[158:159], v[112:113], v[118:119] op_sel_hi:[1,0,1]
	v_cvt_pk_f32_fp8_e32 v[112:113], v98
	v_cvt_pk_f32_fp8_sdwa v[118:119], v98 src0_sel:WORD_1
	v_cvt_pk_f32_fp8_e32 v[124:125], v99
	v_cvt_pk_f32_fp8_sdwa v[98:99], v99 src0_sel:WORD_1
	s_waitcnt lgkmcnt(0)
	v_pk_fma_f32 v[100:101], v[100:101], v[108:109], v[104:105] op_sel_hi:[1,0,1]
	ds_bpermute_b32 v104, v168, v180
	v_pk_fma_f32 v[112:113], v[112:113], v[108:109], v[116:117] op_sel_hi:[1,0,1]
	v_pk_fma_f32 v[116:117], v[118:119], v[108:109], v[120:121] op_sel_hi:[1,0,1]
	v_pk_fma_f32 v[118:119], v[124:125], v[108:109], v[122:123] op_sel_hi:[1,0,1]
	v_pk_fma_f32 v[98:99], v[98:99], v[108:109], v[102:103] op_sel_hi:[1,0,1]
	v_pk_fma_f32 v[102:103], v[126:127], v[108:109], v[106:107] op_sel_hi:[1,0,1]
	s_waitcnt vmcnt(28)
	v_cvt_pk_f32_fp8_e32 v[122:123], v96
	v_cvt_pk_f32_fp8_sdwa v[124:125], v96 src0_sel:WORD_1
	v_cvt_pk_f32_fp8_e32 v[126:127], v97
	v_cvt_pk_f32_fp8_sdwa v[96:97], v97 src0_sel:WORD_1
	v_pk_fma_f32 v[106:107], v[128:129], v[108:109], v[110:111] op_sel_hi:[1,0,1]
	v_pk_fma_f32 v[110:111], v[154:155], v[108:109], v[114:115] op_sel_hi:[1,0,1]
	v_cvt_pk_f32_fp8_e32 v[108:109], v94
	v_cvt_pk_f32_fp8_sdwa v[114:115], v94 src0_sel:WORD_1
	v_cvt_pk_f32_fp8_e32 v[120:121], v95
	v_cvt_pk_f32_fp8_sdwa v[94:95], v95 src0_sel:WORD_1
	s_waitcnt lgkmcnt(0)
	v_pk_fma_f32 v[96:97], v[96:97], v[104:105], v[100:101] op_sel_hi:[1,0,1]
	ds_bpermute_b32 v100, v169, v180
	v_pk_fma_f32 v[108:109], v[108:109], v[104:105], v[112:113] op_sel_hi:[1,0,1]
	v_pk_fma_f32 v[112:113], v[114:115], v[104:105], v[116:117] op_sel_hi:[1,0,1]
	v_pk_fma_f32 v[114:115], v[120:121], v[104:105], v[118:119] op_sel_hi:[1,0,1]
	v_pk_fma_f32 v[94:95], v[94:95], v[104:105], v[98:99] op_sel_hi:[1,0,1]
	v_pk_fma_f32 v[98:99], v[122:123], v[104:105], v[102:103] op_sel_hi:[1,0,1]
	s_waitcnt vmcnt(27)
	v_cvt_pk_f32_fp8_e32 v[118:119], v92
	v_cvt_pk_f32_fp8_sdwa v[120:121], v92 src0_sel:WORD_1
	v_cvt_pk_f32_fp8_e32 v[122:123], v93
	v_cvt_pk_f32_fp8_sdwa v[92:93], v93 src0_sel:WORD_1
	v_pk_fma_f32 v[102:103], v[124:125], v[104:105], v[106:107] op_sel_hi:[1,0,1]
	v_pk_fma_f32 v[106:107], v[126:127], v[104:105], v[110:111] op_sel_hi:[1,0,1]
	v_cvt_pk_f32_fp8_e32 v[104:105], v90
	v_cvt_pk_f32_fp8_sdwa v[110:111], v90 src0_sel:WORD_1
	v_cvt_pk_f32_fp8_e32 v[116:117], v91
	v_cvt_pk_f32_fp8_sdwa v[90:91], v91 src0_sel:WORD_1
	s_waitcnt lgkmcnt(0)
	v_pk_fma_f32 v[92:93], v[92:93], v[100:101], v[96:97] op_sel_hi:[1,0,1]
	ds_bpermute_b32 v96, v170, v180
	v_pk_fma_f32 v[104:105], v[104:105], v[100:101], v[108:109] op_sel_hi:[1,0,1]
	v_pk_fma_f32 v[108:109], v[110:111], v[100:101], v[112:113] op_sel_hi:[1,0,1]
	v_pk_fma_f32 v[110:111], v[116:117], v[100:101], v[114:115] op_sel_hi:[1,0,1]
	v_pk_fma_f32 v[90:91], v[90:91], v[100:101], v[94:95] op_sel_hi:[1,0,1]
	v_pk_fma_f32 v[94:95], v[118:119], v[100:101], v[98:99] op_sel_hi:[1,0,1]
	s_waitcnt vmcnt(26)
; DI void ev_compute(const uint4 (&v)[16], const float c0, const float c1, u16* __restrict__ yrow, const int lane) {
;   f32x2 acc[8];
; #pragma unroll
;   for (int k = 0; k < 8; ++k) acc[k] = f32x2{0.f, 0.f};
; #pragma unroll
;   for (int i = 0; i < 16; ++i) {
;     const float c = __shfl(i < 8 ? c0 : c1, (8 * i + (lane >> 3)) & 63, 64);
;     const f32x2 cc = f32x2{c, c};
;     f32x2 vf[8];
;     fp8x16_to_f32(v[i], vf);
; #pragma unroll
;     for (int k = 0; k < 8; ++k) acc[k] = __builtin_elementwise_fma(vf[k], cc, acc[k]);
;   }
	v_cvt_pk_f32_fp8_e32 v[114:115], v88
	v_cvt_pk_f32_fp8_sdwa v[116:117], v88 src0_sel:WORD_1
	v_cvt_pk_f32_fp8_e32 v[118:119], v89
	v_cvt_pk_f32_fp8_sdwa v[88:89], v89 src0_sel:WORD_1
	v_pk_fma_f32 v[98:99], v[120:121], v[100:101], v[102:103] op_sel_hi:[1,0,1]
	v_pk_fma_f32 v[102:103], v[122:123], v[100:101], v[106:107] op_sel_hi:[1,0,1]
	v_cvt_pk_f32_fp8_e32 v[100:101], v86
	v_cvt_pk_f32_fp8_sdwa v[106:107], v86 src0_sel:WORD_1
	v_cvt_pk_f32_fp8_e32 v[112:113], v87
	v_cvt_pk_f32_fp8_sdwa v[86:87], v87 src0_sel:WORD_1
	s_waitcnt lgkmcnt(0)
	v_pk_fma_f32 v[88:89], v[88:89], v[96:97], v[92:93] op_sel_hi:[1,0,1]
	ds_bpermute_b32 v92, v171, v180
	v_pk_fma_f32 v[100:101], v[100:101], v[96:97], v[104:105] op_sel_hi:[1,0,1]
	v_pk_fma_f32 v[104:105], v[106:107], v[96:97], v[108:109] op_sel_hi:[1,0,1]
	v_pk_fma_f32 v[106:107], v[112:113], v[96:97], v[110:111] op_sel_hi:[1,0,1]
	v_pk_fma_f32 v[86:87], v[86:87], v[96:97], v[90:91] op_sel_hi:[1,0,1]
	v_pk_fma_f32 v[90:91], v[114:115], v[96:97], v[94:95] op_sel_hi:[1,0,1]
	s_waitcnt vmcnt(25)
	v_cvt_pk_f32_fp8_e32 v[110:111], v84
	v_cvt_pk_f32_fp8_sdwa v[112:113], v84 src0_sel:WORD_1
	v_cvt_pk_f32_fp8_e32 v[114:115], v85
	v_cvt_pk_f32_fp8_sdwa v[84:85], v85 src0_sel:WORD_1
	v_pk_fma_f32 v[94:95], v[116:117], v[96:97], v[98:99] op_sel_hi:[1,0,1]
	v_pk_fma_f32 v[98:99], v[118:119], v[96:97], v[102:103] op_sel_hi:[1,0,1]
	v_cvt_pk_f32_fp8_e32 v[96:97], v82
	v_cvt_pk_f32_fp8_sdwa v[102:103], v82 src0_sel:WORD_1
	v_cvt_pk_f32_fp8_e32 v[108:109], v83
	v_cvt_pk_f32_fp8_sdwa v[82:83], v83 src0_sel:WORD_1
	s_waitcnt lgkmcnt(0)
	v_pk_fma_f32 v[84:85], v[84:85], v[92:93], v[88:89] op_sel_hi:[1,0,1]
	ds_bpermute_b32 v88, v172, v180
	v_pk_fma_f32 v[96:97], v[96:97], v[92:93], v[100:101] op_sel_hi:[1,0,1]
	v_pk_fma_f32 v[100:101], v[102:103], v[92:93], v[104:105] op_sel_hi:[1,0,1]
	v_pk_fma_f32 v[102:103], v[108:109], v[92:93], v[106:107] op_sel_hi:[1,0,1]
	v_pk_fma_f32 v[82:83], v[82:83], v[92:93], v[86:87] op_sel_hi:[1,0,1]
	v_pk_fma_f32 v[86:87], v[110:111], v[92:93], v[90:91] op_sel_hi:[1,0,1]
	s_waitcnt vmcnt(24)
	v_cvt_pk_f32_fp8_e32 v[106:107], v80
	v_cvt_pk_f32_fp8_sdwa v[108:109], v80 src0_sel:WORD_1
	v_cvt_pk_f32_fp8_e32 v[110:111], v81
	v_cvt_pk_f32_fp8_sdwa v[80:81], v81 src0_sel:WORD_1
	v_pk_fma_f32 v[90:91], v[112:113], v[92:93], v[94:95] op_sel_hi:[1,0,1]
	v_pk_fma_f32 v[94:95], v[114:115], v[92:93], v[98:99] op_sel_hi:[1,0,1]
	v_cvt_pk_f32_fp8_e32 v[92:93], v78
	v_cvt_pk_f32_fp8_sdwa v[98:99], v78 src0_sel:WORD_1
	v_cvt_pk_f32_fp8_e32 v[104:105], v79
	v_cvt_pk_f32_fp8_sdwa v[78:79], v79 src0_sel:WORD_1
	s_waitcnt lgkmcnt(0)
	v_pk_fma_f32 v[80:81], v[80:81], v[88:89], v[84:85] op_sel_hi:[1,0,1]
	ds_bpermute_b32 v84, v173, v180
	v_pk_fma_f32 v[92:93], v[92:93], v[88:89], v[96:97] op_sel_hi:[1,0,1]
	v_pk_fma_f32 v[96:97], v[98:99], v[88:89], v[100:101] op_sel_hi:[1,0,1]
	v_pk_fma_f32 v[98:99], v[104:105], v[88:89], v[102:103] op_sel_hi:[1,0,1]
	v_pk_fma_f32 v[78:79], v[78:79], v[88:89], v[82:83] op_sel_hi:[1,0,1]
	v_pk_fma_f32 v[82:83], v[106:107], v[88:89], v[86:87] op_sel_hi:[1,0,1]
	s_waitcnt vmcnt(23)
	v_cvt_pk_f32_fp8_e32 v[102:103], v76
	v_cvt_pk_f32_fp8_sdwa v[104:105], v76 src0_sel:WORD_1
	v_cvt_pk_f32_fp8_e32 v[106:107], v77
	v_cvt_pk_f32_fp8_sdwa v[76:77], v77 src0_sel:WORD_1
	v_pk_fma_f32 v[86:87], v[108:109], v[88:89], v[90:91] op_sel_hi:[1,0,1]
	v_pk_fma_f32 v[90:91], v[110:111], v[88:89], v[94:95] op_sel_hi:[1,0,1]
	v_cvt_pk_f32_fp8_e32 v[88:89], v74
	v_cvt_pk_f32_fp8_sdwa v[94:95], v74 src0_sel:WORD_1
	v_cvt_pk_f32_fp8_e32 v[100:101], v75
	v_cvt_pk_f32_fp8_sdwa v[74:75], v75 src0_sel:WORD_1
	s_waitcnt lgkmcnt(0)
	v_pk_fma_f32 v[76:77], v[76:77], v[84:85], v[80:81] op_sel_hi:[1,0,1]
	ds_bpermute_b32 v80, v175, v180
	v_pk_fma_f32 v[88:89], v[88:89], v[84:85], v[92:93] op_sel_hi:[1,0,1]
	v_pk_fma_f32 v[92:93], v[94:95], v[84:85], v[96:97] op_sel_hi:[1,0,1]
	v_pk_fma_f32 v[94:95], v[100:101], v[84:85], v[98:99] op_sel_hi:[1,0,1]
	v_pk_fma_f32 v[74:75], v[74:75], v[84:85], v[78:79] op_sel_hi:[1,0,1]
	v_pk_fma_f32 v[78:79], v[102:103], v[84:85], v[82:83] op_sel_hi:[1,0,1]
	s_waitcnt vmcnt(22)
; DI unsigned pack2(float a, float b) { const f32x2 v = {a, b}; const bf16x2_t r = __builtin_convertvector(v, bf16x2_t); return __builtin_bit_cast(unsigned, r); }
; DI void ev_compute(const uint4 (&v)[16], const float c0, const float c1, u16* __restrict__ yrow, const int lane) {
;   f32x2 acc[8];
; #pragma unroll
;   for (int k = 0; k < 8; ++k) acc[k] = f32x2{0.f, 0.f};
; #pragma unroll
;   for (int i = 0; i < 16; ++i) {
;     const float c = __shfl(i < 8 ? c0 : c1, (8 * i + (lane >> 3)) & 63, 64);
;     const f32x2 cc = f32x2{c, c};
;     f32x2 vf[8];
;     fp8x16_to_f32(v[i], vf);
; #pragma unroll
;     for (int k = 0; k < 8; ++k) acc[k] = __builtin_elementwise_fma(vf[k], cc, acc[k]);
;   }
;   float a[16];
; #pragma unroll
;   for (int k = 0; k < 8; ++k) { a[2 * k] = acc[k][0]; a[2 * k + 1] = acc[k][1]; }
;   float q8[8], q4[4], q2[2];
;   const bool b5 = lane & 32, b4 = lane & 16, b3 = lane & 8;
; #pragma unroll
;   for (int j = 0; j < 8; ++j) { const float keep = b5 ? a[8 + j] : a[j], send = b5 ? a[j] : a[8 + j]; q8[j] = keep + __shfl_xor(send, 32, 64); }
; #pragma unroll
;   for (int j = 0; j < 4; ++j) { const float keep = b4 ? q8[4 + j] : q8[j], send = b4 ? q8[j] : q8[4 + j]; q4[j] = keep + __shfl_xor(send, 16, 64); }
; #pragma unroll
;   for (int j = 0; j < 2; ++j) { const float keep = b3 ? q4[2 + j] : q4[j], send = b3 ? q4[j] : q4[2 + j]; q2[j] = keep + __shfl_xor(send, 8, 64); }
;   *(unsigned*)(yrow + 16 * (lane & 7) + 2 * (lane >> 3)) = pack2(q2[0], q2[1]);
; DI void phase_ev(const Params& p, const unsigned my_xcc, const unsigned my_rank) {
;     ...
;       ev_compute(vB, cb0, cb1, ybuf + (size_t)tB * 1024 + 128 * cs, lane);
;       tA = tA2; a0 = na0; a1 = na1; ca0 = nca0; ca1 = nca1; tB = tB2; b0 = nb0; b1 = nb1; cb0 = ncb0; cb1 = ncb1;
	v_cvt_pk_f32_fp8_e32 v[98:99], v72
	v_cvt_pk_f32_fp8_sdwa v[100:101], v72 src0_sel:WORD_1
	v_cvt_pk_f32_fp8_e32 v[102:103], v73
	v_cvt_pk_f32_fp8_sdwa v[72:73], v73 src0_sel:WORD_1
	v_pk_fma_f32 v[82:83], v[104:105], v[84:85], v[86:87] op_sel_hi:[1,0,1]
	v_pk_fma_f32 v[86:87], v[106:107], v[84:85], v[90:91] op_sel_hi:[1,0,1]
	v_cvt_pk_f32_fp8_e32 v[84:85], v70
	v_cvt_pk_f32_fp8_sdwa v[90:91], v70 src0_sel:WORD_1
	v_cvt_pk_f32_fp8_e32 v[96:97], v71
	v_cvt_pk_f32_fp8_sdwa v[70:71], v71 src0_sel:WORD_1
	s_waitcnt lgkmcnt(0)
	v_pk_fma_f32 v[72:73], v[72:73], v[80:81], v[76:77] op_sel_hi:[1,0,1]
	ds_bpermute_b32 v76, v176, v180
	v_pk_fma_f32 v[84:85], v[84:85], v[80:81], v[88:89] op_sel_hi:[1,0,1]
	v_pk_fma_f32 v[88:89], v[90:91], v[80:81], v[92:93] op_sel_hi:[1,0,1]
	v_pk_fma_f32 v[90:91], v[96:97], v[80:81], v[94:95] op_sel_hi:[1,0,1]
	v_pk_fma_f32 v[70:71], v[70:71], v[80:81], v[74:75] op_sel_hi:[1,0,1]
	v_pk_fma_f32 v[74:75], v[98:99], v[80:81], v[78:79] op_sel_hi:[1,0,1]
	v_pk_fma_f32 v[78:79], v[100:101], v[80:81], v[82:83] op_sel_hi:[1,0,1]
	v_pk_fma_f32 v[82:83], v[102:103], v[80:81], v[86:87] op_sel_hi:[1,0,1]
	s_waitcnt vmcnt(21)
	v_cvt_pk_f32_fp8_e32 v[80:81], v66
	v_cvt_pk_f32_fp8_sdwa v[86:87], v66 src0_sel:WORD_1
	v_cvt_pk_f32_fp8_e32 v[92:93], v67
	v_cvt_pk_f32_fp8_sdwa v[66:67], v67 src0_sel:WORD_1
	v_cvt_pk_f32_fp8_e32 v[94:95], v68
	v_cvt_pk_f32_fp8_sdwa v[96:97], v68 src0_sel:WORD_1
	v_cvt_pk_f32_fp8_e32 v[98:99], v69
	v_cvt_pk_f32_fp8_sdwa v[68:69], v69 src0_sel:WORD_1
	s_waitcnt lgkmcnt(0)
	v_pk_fma_f32 v[80:81], v[80:81], v[76:77], v[84:85] op_sel_hi:[1,0,1]
	v_pk_fma_f32 v[66:67], v[66:67], v[76:77], v[70:71] op_sel_hi:[1,0,1]
	v_pk_fma_f32 v[70:71], v[94:95], v[76:77], v[74:75] op_sel_hi:[1,0,1]
	v_pk_fma_f32 v[84:85], v[86:87], v[76:77], v[88:89] op_sel_hi:[1,0,1]
	v_pk_fma_f32 v[86:87], v[92:93], v[76:77], v[90:91] op_sel_hi:[1,0,1]
	v_pk_fma_f32 v[74:75], v[96:97], v[76:77], v[78:79] op_sel_hi:[1,0,1]
	v_pk_fma_f32 v[78:79], v[98:99], v[76:77], v[82:83] op_sel_hi:[1,0,1]
	v_pk_fma_f32 v[68:69], v[68:69], v[76:77], v[72:73] op_sel_hi:[1,0,1]
	v_cndmask_b32_e64 v72, v80, v70, s[6:7]
	v_cndmask_b32_e64 v73, v81, v71, s[6:7]
	ds_bpermute_b32 v72, v177, v72
	ds_bpermute_b32 v73, v177, v73
	v_cndmask_b32_e64 v76, v84, v74, s[6:7]
	v_cndmask_b32_e64 v77, v85, v75, s[6:7]
	v_cndmask_b32_e64 v82, v86, v78, s[6:7]
	v_cndmask_b32_e64 v83, v87, v79, s[6:7]
	v_cndmask_b32_e64 v88, v66, v68, s[6:7]
	v_cndmask_b32_e64 v89, v67, v69, s[6:7]
	ds_bpermute_b32 v76, v177, v76
	ds_bpermute_b32 v77, v177, v77
	ds_bpermute_b32 v82, v177, v82
	ds_bpermute_b32 v83, v177, v83
	ds_bpermute_b32 v88, v177, v88
	ds_bpermute_b32 v89, v177, v89
	v_cndmask_b32_e64 v71, v71, v81, s[6:7]
	v_cndmask_b32_e64 v70, v70, v80, s[6:7]
	s_waitcnt lgkmcnt(6)
	v_pk_add_f32 v[70:71], v[70:71], v[72:73]
	v_cndmask_b32_e64 v73, v75, v85, s[6:7]
	v_cndmask_b32_e64 v72, v74, v84, s[6:7]
	v_cndmask_b32_e64 v75, v79, v87, s[6:7]
	v_cndmask_b32_e64 v74, v78, v86, s[6:7]
	v_cndmask_b32_e64 v67, v69, v67, s[6:7]
	v_cndmask_b32_e64 v66, v68, v66, s[6:7]
	s_waitcnt lgkmcnt(4)
	v_pk_add_f32 v[72:73], v[72:73], v[76:77]
	s_waitcnt lgkmcnt(2)
	v_pk_add_f32 v[74:75], v[74:75], v[82:83]
	s_waitcnt lgkmcnt(0)
	v_pk_add_f32 v[66:67], v[66:67], v[88:89]
	v_cndmask_b32_e64 v68, v70, v74, s[8:9]
	v_cndmask_b32_e64 v76, v74, v70, s[8:9]
	v_cndmask_b32_e64 v69, v71, v75, s[8:9]
	v_cndmask_b32_e64 v70, v72, v66, s[8:9]
	v_cndmask_b32_e64 v74, v66, v72, s[8:9]
	v_cndmask_b32_e64 v66, v73, v67, s[8:9]
	ds_bpermute_b32 v68, v178, v68
	v_cndmask_b32_e64 v77, v75, v71, s[8:9]
	ds_bpermute_b32 v69, v178, v69
	ds_bpermute_b32 v70, v178, v70
	ds_bpermute_b32 v71, v178, v66
	v_cndmask_b32_e64 v75, v67, v73, s[8:9]
	v_mov_b32_e32 v155, v181
	s_waitcnt lgkmcnt(2)
	v_pk_add_f32 v[68:69], v[76:77], v[68:69]
	v_mov_b32_e32 v154, v182
	s_waitcnt lgkmcnt(0)
	v_pk_add_f32 v[66:67], v[74:75], v[70:71]
	s_waitcnt vmcnt(0)
	v_mov_b32_e32 v180, v187
	v_cndmask_b32_e64 v70, v68, v66, s[10:11]
	v_cndmask_b32_e64 v72, v66, v68, s[10:11]
	v_cndmask_b32_e64 v66, v69, v67, s[10:11]
	ds_bpermute_b32 v70, v179, v70
	ds_bpermute_b32 v71, v179, v66
	v_cndmask_b32_e64 v73, v67, v69, s[10:11]
	v_mov_b32_e32 v183, v186
	s_waitcnt lgkmcnt(0)
	v_pk_add_f32 v[66:67], v[72:73], v[70:71]
	s_nop 0
	v_cvt_pk_bf16_f32 v68, v66, v67
	v_lshl_add_u64 v[66:67], v[152:153], 0, s[30:31]
	s_mov_b32 s30, s34
	global_store_dword v[66:67], v68, off
	s_cbranch_scc1 .LBB0_570
	s_branch .LBB0_566
